# v15 plus: GEMM K-loop mid-block setprio 0/1 flips and already-satisfied lgkmcnt waits removed
# speedup vs baseline: 1.0032x; 1.0032x over previous
.LBB0_252:
	ds_read_b128 v[156:159], v149
	ds_read_b128 v[160:163], v149 offset:1024
	ds_read_b128 v[164:167], v149 offset:2048
	ds_read_b128 v[168:171], v149 offset:3072
	ds_read_b128 v[172:175], v150
	ds_read_b128 v[176:179], v150 offset:1024
	ds_read_b128 v[180:183], v150 offset:2048
	ds_read_b128 v[184:187], v150 offset:3072
	s_add_u32 s26, s24, 0xfffc0080
	s_addc_u32 s27, s25, -1
	s_cmp_eq_u32 s57, 12
	s_cselect_b32 s29, s19, s27
	s_cselect_b32 s28, s53, s26
	s_cselect_b32 s27, s17, s56
	s_cselect_b32 s26, s54, s55
	v_lshl_add_u64 v[146:147], s[24:25], 0, v[138:139]
	s_add_i32 m0, s38, 0xc000
	ds_read_b128 v[188:191], v151
	ds_read_b128 v[192:195], v151 offset:1024
	ds_read_b128 v[196:199], v151 offset:2048
	ds_read_b128 v[200:203], v151 offset:3072
	ds_read_b128 v[204:207], v151 offset:4096
	ds_read_b128 v[208:211], v151 offset:5120
	ds_read_b128 v[212:215], v151 offset:6144
	ds_read_b128 v[216:219], v151 offset:7168
	global_load_lds_dwordx4 v[146:147], off
	v_lshl_add_u64 v[146:147], s[24:25], 0, v[140:141]
	s_add_i32 m0, s38, 0xe000
	s_nop 0
	global_load_lds_dwordx4 v[146:147], off
	s_waitcnt vmcnt(8)
	s_waitcnt lgkmcnt(0)
	s_barrier
	s_setprio 1
	v_mfma_f32_16x16x32_bf16 v[122:125], v[156:159], v[188:191], v[122:125]
	v_mfma_f32_16x16x32_bf16 v[114:117], v[164:167], v[188:191], v[114:117]
	v_mfma_f32_16x16x32_bf16 v[106:109], v[156:159], v[196:199], v[106:109]
	v_mfma_f32_16x16x32_bf16 v[102:105], v[164:167], v[196:199], v[102:105]
	v_mfma_f32_16x16x32_bf16 v[90:93], v[156:159], v[204:207], v[90:93]
	v_mfma_f32_16x16x32_bf16 v[86:89], v[164:167], v[204:207], v[86:89]
	v_mfma_f32_16x16x32_bf16 v[74:77], v[156:159], v[212:215], v[74:77]
	v_mfma_f32_16x16x32_bf16 v[70:73], v[164:167], v[212:215], v[70:73]
	v_mfma_f32_16x16x32_bf16 v[122:125], v[160:163], v[192:195], v[122:125]
	v_mfma_f32_16x16x32_bf16 v[114:117], v[168:171], v[192:195], v[114:117]
	v_mfma_f32_16x16x32_bf16 v[106:109], v[160:163], v[200:203], v[106:109]
	v_mfma_f32_16x16x32_bf16 v[102:105], v[168:171], v[200:203], v[102:105]
	v_mfma_f32_16x16x32_bf16 v[90:93], v[160:163], v[208:211], v[90:93]
	v_mfma_f32_16x16x32_bf16 v[86:89], v[168:171], v[208:211], v[86:89]
	v_mfma_f32_16x16x32_bf16 v[74:77], v[160:163], v[216:219], v[74:77]
	v_mfma_f32_16x16x32_bf16 v[70:73], v[168:171], v[216:219], v[70:73]
	v_mfma_f32_16x16x32_bf16 v[126:129], v[172:175], v[188:191], v[126:129]
	v_mfma_f32_16x16x32_bf16 v[118:121], v[180:183], v[188:191], v[118:121]
	v_mfma_f32_16x16x32_bf16 v[110:113], v[172:175], v[196:199], v[110:113]
	v_mfma_f32_16x16x32_bf16 v[98:101], v[180:183], v[196:199], v[98:101]
	v_mfma_f32_16x16x32_bf16 v[94:97], v[172:175], v[204:207], v[94:97]
	v_mfma_f32_16x16x32_bf16 v[82:85], v[180:183], v[204:207], v[82:85]
	v_mfma_f32_16x16x32_bf16 v[78:81], v[172:175], v[212:215], v[78:81]
	v_mfma_f32_16x16x32_bf16 v[66:69], v[180:183], v[212:215], v[66:69]
	v_mfma_f32_16x16x32_bf16 v[126:129], v[176:179], v[192:195], v[126:129]
	v_mfma_f32_16x16x32_bf16 v[118:121], v[184:187], v[192:195], v[118:121]
	v_mfma_f32_16x16x32_bf16 v[110:113], v[176:179], v[200:203], v[110:113]
	v_mfma_f32_16x16x32_bf16 v[98:101], v[184:187], v[200:203], v[98:101]
	v_mfma_f32_16x16x32_bf16 v[94:97], v[176:179], v[208:211], v[94:97]
	v_mfma_f32_16x16x32_bf16 v[82:85], v[184:187], v[208:211], v[82:85]
	v_mfma_f32_16x16x32_bf16 v[78:81], v[176:179], v[216:219], v[78:81]
	v_mfma_f32_16x16x32_bf16 v[66:69], v[184:187], v[216:219], v[66:69]
	s_setprio 0
	s_barrier
	s_add_i32 s58, s47, s35
	v_lshl_add_u64 v[146:147], s[26:27], 0, v[134:135]
	s_mov_b32 m0, s58
	ds_read_b128 v[188:191], v151 offset:16384
	ds_read_b128 v[192:195], v151 offset:17408
	ds_read_b128 v[196:199], v151 offset:18432
	ds_read_b128 v[200:203], v151 offset:19456
	ds_read_b128 v[204:207], v151 offset:20480
	ds_read_b128 v[208:211], v151 offset:21504
	ds_read_b128 v[212:215], v151 offset:22528
	ds_read_b128 v[216:219], v151 offset:23552
	global_load_lds_dwordx4 v[146:147], off
	s_add_i32 m0, s58, 0x2000
	s_add_u32 s58, s26, 0x40000
	v_lshl_add_u64 v[220:221], s[26:27], 0, v[130:131]
	s_addc_u32 s59, s27, 0
	s_add_i32 s60, s48, s35
	global_load_lds_dwordx4 v[220:221], off
	v_lshl_add_u64 v[222:223], s[58:59], 0, v[134:135]
	s_mov_b32 m0, s60
	v_lshl_add_u64 v[224:225], s[28:29], 0, v[132:133]
	global_load_lds_dwordx4 v[222:223], off
	v_lshl_add_u64 v[222:223], s[58:59], 0, v[130:131]
	s_add_i32 m0, s60, 0x2000
	s_nop 0
	global_load_lds_dwordx4 v[222:223], off
	v_lshl_add_u64 v[222:223], s[28:29], 0, v[136:137]
	s_mov_b32 m0, s38
	s_nop 0
	global_load_lds_dwordx4 v[222:223], off
	s_mov_b32 m0, s39
	s_nop 0
	global_load_lds_dwordx4 v[224:225], off
	s_waitcnt vmcnt(8)
	s_waitcnt lgkmcnt(0)
	s_barrier
	s_setprio 1
	v_mfma_f32_16x16x32_bf16 v[58:61], v[156:159], v[188:191], v[58:61]
	v_mfma_f32_16x16x32_bf16 v[54:57], v[164:167], v[188:191], v[54:57]
	v_mfma_f32_16x16x32_bf16 v[42:45], v[156:159], v[196:199], v[42:45]
	v_mfma_f32_16x16x32_bf16 v[38:41], v[164:167], v[196:199], v[38:41]
	v_mfma_f32_16x16x32_bf16 v[26:29], v[156:159], v[204:207], v[26:29]
	v_mfma_f32_16x16x32_bf16 v[22:25], v[164:167], v[204:207], v[22:25]
	v_mfma_f32_16x16x32_bf16 v[14:17], v[156:159], v[212:215], v[14:17]
	v_mfma_f32_16x16x32_bf16 v[6:9], v[164:167], v[212:215], v[6:9]
	v_mfma_f32_16x16x32_bf16 v[58:61], v[160:163], v[192:195], v[58:61]
	v_mfma_f32_16x16x32_bf16 v[54:57], v[168:171], v[192:195], v[54:57]
	v_mfma_f32_16x16x32_bf16 v[42:45], v[160:163], v[200:203], v[42:45]
	v_mfma_f32_16x16x32_bf16 v[38:41], v[168:171], v[200:203], v[38:41]
	v_mfma_f32_16x16x32_bf16 v[26:29], v[160:163], v[208:211], v[26:29]
	v_mfma_f32_16x16x32_bf16 v[22:25], v[168:171], v[208:211], v[22:25]
	v_mfma_f32_16x16x32_bf16 v[14:17], v[160:163], v[216:219], v[14:17]
	v_mfma_f32_16x16x32_bf16 v[6:9], v[168:171], v[216:219], v[6:9]
	v_mfma_f32_16x16x32_bf16 v[62:65], v[172:175], v[188:191], v[62:65]
	v_mfma_f32_16x16x32_bf16 v[50:53], v[180:183], v[188:191], v[50:53]
	v_mfma_f32_16x16x32_bf16 v[46:49], v[172:175], v[196:199], v[46:49]
	v_mfma_f32_16x16x32_bf16 v[34:37], v[180:183], v[196:199], v[34:37]
	v_mfma_f32_16x16x32_bf16 v[30:33], v[172:175], v[204:207], v[30:33]
	v_mfma_f32_16x16x32_bf16 v[18:21], v[180:183], v[204:207], v[18:21]
	v_mfma_f32_16x16x32_bf16 v[10:13], v[172:175], v[212:215], v[10:13]
	v_mfma_f32_16x16x32_bf16 v[2:5], v[180:183], v[212:215], v[2:5]
	v_mfma_f32_16x16x32_bf16 v[62:65], v[176:179], v[192:195], v[62:65]
	v_mfma_f32_16x16x32_bf16 v[50:53], v[184:187], v[192:195], v[50:53]
	v_mfma_f32_16x16x32_bf16 v[46:49], v[176:179], v[200:203], v[46:49]
	v_mfma_f32_16x16x32_bf16 v[34:37], v[184:187], v[200:203], v[34:37]
	v_mfma_f32_16x16x32_bf16 v[30:33], v[176:179], v[208:211], v[30:33]
	v_mfma_f32_16x16x32_bf16 v[18:21], v[184:187], v[208:211], v[18:21]
	v_mfma_f32_16x16x32_bf16 v[10:13], v[176:179], v[216:219], v[10:13]
	v_mfma_f32_16x16x32_bf16 v[2:5], v[184:187], v[216:219], v[2:5]
	s_setprio 0
	s_barrier
	ds_read_b128 v[156:159], v154
	ds_read_b128 v[160:163], v154 offset:1024
	ds_read_b128 v[164:167], v154 offset:2048
	ds_read_b128 v[168:171], v154 offset:3072
	ds_read_b128 v[172:175], v155
	ds_read_b128 v[176:179], v155 offset:1024
	ds_read_b128 v[180:183], v155 offset:2048
	ds_read_b128 v[184:187], v155 offset:3072
	s_add_u32 s28, s28, 0x40000
	s_addc_u32 s29, s29, 0
	s_mov_b32 m0, s40
	v_lshl_add_u64 v[226:227], s[28:29], 0, v[136:137]
	ds_read_b128 v[188:191], v151 offset:32768
	ds_read_b128 v[192:195], v151 offset:33792
	ds_read_b128 v[196:199], v151 offset:34816
	ds_read_b128 v[200:203], v151 offset:35840
	ds_read_b128 v[204:207], v151 offset:36864
	ds_read_b128 v[208:211], v151 offset:37888
	ds_read_b128 v[212:215], v151 offset:38912
	ds_read_b128 v[216:219], v151 offset:39936
	global_load_lds_dwordx4 v[226:227], off
	v_lshl_add_u64 v[226:227], s[28:29], 0, v[132:133]
	s_mov_b32 m0, s41
	s_nop 0
	global_load_lds_dwordx4 v[226:227], off
	s_waitcnt vmcnt(8)
	s_waitcnt lgkmcnt(0)
	s_barrier
	s_setprio 1
	v_mfma_f32_16x16x32_bf16 v[122:125], v[156:159], v[188:191], v[122:125]
	v_mfma_f32_16x16x32_bf16 v[114:117], v[164:167], v[188:191], v[114:117]
	v_mfma_f32_16x16x32_bf16 v[106:109], v[156:159], v[196:199], v[106:109]
	v_mfma_f32_16x16x32_bf16 v[102:105], v[164:167], v[196:199], v[102:105]
	v_mfma_f32_16x16x32_bf16 v[90:93], v[156:159], v[204:207], v[90:93]
	v_mfma_f32_16x16x32_bf16 v[86:89], v[164:167], v[204:207], v[86:89]
	v_mfma_f32_16x16x32_bf16 v[74:77], v[156:159], v[212:215], v[74:77]
	v_mfma_f32_16x16x32_bf16 v[70:73], v[164:167], v[212:215], v[70:73]
	v_mfma_f32_16x16x32_bf16 v[122:125], v[160:163], v[192:195], v[122:125]
	v_mfma_f32_16x16x32_bf16 v[114:117], v[168:171], v[192:195], v[114:117]
	v_mfma_f32_16x16x32_bf16 v[106:109], v[160:163], v[200:203], v[106:109]
	v_mfma_f32_16x16x32_bf16 v[102:105], v[168:171], v[200:203], v[102:105]
	v_mfma_f32_16x16x32_bf16 v[90:93], v[160:163], v[208:211], v[90:93]
	v_mfma_f32_16x16x32_bf16 v[86:89], v[168:171], v[208:211], v[86:89]
	v_mfma_f32_16x16x32_bf16 v[74:77], v[160:163], v[216:219], v[74:77]
	v_mfma_f32_16x16x32_bf16 v[70:73], v[168:171], v[216:219], v[70:73]
	v_mfma_f32_16x16x32_bf16 v[126:129], v[172:175], v[188:191], v[126:129]
	v_mfma_f32_16x16x32_bf16 v[118:121], v[180:183], v[188:191], v[118:121]
	v_mfma_f32_16x16x32_bf16 v[110:113], v[172:175], v[196:199], v[110:113]
	v_mfma_f32_16x16x32_bf16 v[98:101], v[180:183], v[196:199], v[98:101]
	v_mfma_f32_16x16x32_bf16 v[94:97], v[172:175], v[204:207], v[94:97]
	v_mfma_f32_16x16x32_bf16 v[82:85], v[180:183], v[204:207], v[82:85]
	v_mfma_f32_16x16x32_bf16 v[78:81], v[172:175], v[212:215], v[78:81]
	v_mfma_f32_16x16x32_bf16 v[66:69], v[180:183], v[212:215], v[66:69]
	v_mfma_f32_16x16x32_bf16 v[126:129], v[176:179], v[192:195], v[126:129]
	v_mfma_f32_16x16x32_bf16 v[118:121], v[184:187], v[192:195], v[118:121]
	v_mfma_f32_16x16x32_bf16 v[110:113], v[176:179], v[200:203], v[110:113]
	v_mfma_f32_16x16x32_bf16 v[98:101], v[184:187], v[200:203], v[98:101]
	v_mfma_f32_16x16x32_bf16 v[94:97], v[176:179], v[208:211], v[94:97]
	v_mfma_f32_16x16x32_bf16 v[82:85], v[184:187], v[208:211], v[82:85]
	v_mfma_f32_16x16x32_bf16 v[78:81], v[176:179], v[216:219], v[78:81]
	v_mfma_f32_16x16x32_bf16 v[66:69], v[184:187], v[216:219], v[66:69]
	s_setprio 0
	s_barrier
	s_add_i32 s28, s51, s35
	v_lshl_add_u64 v[146:147], v[146:147], 0, s[12:13]
	s_mov_b32 m0, s28
	ds_read_b128 v[188:191], v151 offset:49152
	ds_read_b128 v[192:195], v151 offset:50176
	ds_read_b128 v[196:199], v151 offset:51200
	ds_read_b128 v[200:203], v151 offset:52224
	ds_read_b128 v[204:207], v151 offset:53248
	ds_read_b128 v[208:211], v151 offset:54272
	ds_read_b128 v[212:215], v151 offset:55296
	ds_read_b128 v[216:219], v151 offset:56320
	global_load_lds_dwordx4 v[146:147], off
	s_add_i32 m0, s28, 0x2000
	s_add_u32 s26, s26, 0x40080
	v_lshl_add_u64 v[146:147], v[220:221], 0, s[12:13]
	s_addc_u32 s27, s27, 0
	s_add_i32 s28, s52, s35
	global_load_lds_dwordx4 v[146:147], off
	v_lshl_add_u64 v[146:147], s[26:27], 0, v[134:135]
	s_mov_b32 m0, s28
	s_nop 0
	global_load_lds_dwordx4 v[146:147], off
	v_lshl_add_u64 v[146:147], s[26:27], 0, v[130:131]
	s_add_i32 m0, s28, 0x2000
	s_nop 0
	global_load_lds_dwordx4 v[146:147], off
	v_lshl_add_u64 v[146:147], v[222:223], 0, s[12:13]
	s_mov_b32 m0, s44
	s_nop 0
	global_load_lds_dwordx4 v[146:147], off
	v_lshl_add_u64 v[146:147], v[224:225], 0, s[12:13]
	s_mov_b32 m0, s45
	s_nop 0
	global_load_lds_dwordx4 v[146:147], off
	s_waitcnt vmcnt(8)
	s_waitcnt lgkmcnt(0)
	s_barrier
	s_setprio 1
	v_mfma_f32_16x16x32_bf16 v[58:61], v[156:159], v[188:191], v[58:61]
	v_mfma_f32_16x16x32_bf16 v[54:57], v[164:167], v[188:191], v[54:57]
	v_mfma_f32_16x16x32_bf16 v[42:45], v[156:159], v[196:199], v[42:45]
	v_mfma_f32_16x16x32_bf16 v[38:41], v[164:167], v[196:199], v[38:41]
	v_mfma_f32_16x16x32_bf16 v[26:29], v[156:159], v[204:207], v[26:29]
	v_mfma_f32_16x16x32_bf16 v[22:25], v[164:167], v[204:207], v[22:25]
	v_mfma_f32_16x16x32_bf16 v[14:17], v[156:159], v[212:215], v[14:17]
	v_mfma_f32_16x16x32_bf16 v[6:9], v[164:167], v[212:215], v[6:9]
	v_mfma_f32_16x16x32_bf16 v[58:61], v[160:163], v[192:195], v[58:61]
	v_mfma_f32_16x16x32_bf16 v[54:57], v[168:171], v[192:195], v[54:57]
	v_mfma_f32_16x16x32_bf16 v[42:45], v[160:163], v[200:203], v[42:45]
	v_mfma_f32_16x16x32_bf16 v[38:41], v[168:171], v[200:203], v[38:41]
	v_mfma_f32_16x16x32_bf16 v[26:29], v[160:163], v[208:211], v[26:29]
	v_mfma_f32_16x16x32_bf16 v[22:25], v[168:171], v[208:211], v[22:25]
	v_mfma_f32_16x16x32_bf16 v[14:17], v[160:163], v[216:219], v[14:17]
	v_mfma_f32_16x16x32_bf16 v[6:9], v[168:171], v[216:219], v[6:9]
	v_mfma_f32_16x16x32_bf16 v[62:65], v[172:175], v[188:191], v[62:65]
	v_mfma_f32_16x16x32_bf16 v[50:53], v[180:183], v[188:191], v[50:53]
	v_mfma_f32_16x16x32_bf16 v[46:49], v[172:175], v[196:199], v[46:49]
	v_mfma_f32_16x16x32_bf16 v[34:37], v[180:183], v[196:199], v[34:37]
	v_mfma_f32_16x16x32_bf16 v[30:33], v[172:175], v[204:207], v[30:33]
	v_mfma_f32_16x16x32_bf16 v[18:21], v[180:183], v[204:207], v[18:21]
	v_mfma_f32_16x16x32_bf16 v[10:13], v[172:175], v[212:215], v[10:13]
	v_mfma_f32_16x16x32_bf16 v[2:5], v[180:183], v[212:215], v[2:5]
	v_mfma_f32_16x16x32_bf16 v[62:65], v[176:179], v[192:195], v[62:65]
	v_mfma_f32_16x16x32_bf16 v[50:53], v[184:187], v[192:195], v[50:53]
	v_mfma_f32_16x16x32_bf16 v[46:49], v[176:179], v[200:203], v[46:49]
	v_mfma_f32_16x16x32_bf16 v[34:37], v[184:187], v[200:203], v[34:37]
	v_mfma_f32_16x16x32_bf16 v[30:33], v[176:179], v[208:211], v[30:33]
	v_mfma_f32_16x16x32_bf16 v[18:21], v[184:187], v[208:211], v[18:21]
	v_mfma_f32_16x16x32_bf16 v[10:13], v[176:179], v[216:219], v[10:13]
	v_mfma_f32_16x16x32_bf16 v[2:5], v[184:187], v[216:219], v[2:5]
	s_setprio 0
	s_barrier
	s_add_i32 s57, s57, 2
	s_add_u32 s24, s24, 0x100
	s_addc_u32 s25, s25, 0
	s_add_u32 s55, s55, 0x100
	s_addc_u32 s56, s56, 0
	s_cmp_gt_u32 s57, 13
	s_cbranch_scc0 .LBB0_252
	s_and_b64 vcc, exec, s[14:15]
	s_cbranch_vccz .LBB0_255
	s_barrier

.LBB0_294:
	ds_read_b128 v[130:133], v207
	ds_read_b128 v[134:137], v207 offset:1024
	ds_read_b128 v[138:141], v207 offset:2048
	ds_read_b128 v[142:145], v207 offset:3072
	ds_read_b128 v[146:149], v208
	ds_read_b128 v[150:153], v208 offset:1024
	ds_read_b128 v[154:157], v208 offset:2048
	ds_read_b128 v[158:161], v208 offset:3072
	s_add_u32 s20, s18, 0xfff50080
	s_addc_u32 s21, s19, -1
	s_cmp_eq_u32 s51, 40
	s_cselect_b32 s23, s9, s21
	s_cselect_b32 s22, s8, s20
	s_cselect_b32 s21, s11, s50
	s_cselect_b32 s20, s10, s49
	v_lshl_add_u64 v[218:219], s[18:19], 0, v[186:187]
	s_add_i32 m0, s31, 0xc000
	ds_read_b128 v[162:165], v209
	ds_read_b128 v[166:169], v209 offset:1024
	ds_read_b128 v[170:173], v209 offset:2048
	ds_read_b128 v[174:177], v209 offset:3072
	ds_read_b128 v[194:197], v209 offset:4096
	ds_read_b128 v[198:201], v209 offset:5120
	ds_read_b128 v[202:205], v209 offset:6144
	ds_read_b128 v[214:217], v209 offset:7168
	global_load_lds_dwordx4 v[218:219], off
	v_lshl_add_u64 v[218:219], s[18:19], 0, v[188:189]
	s_add_i32 m0, s31, 0xe000
	s_nop 0
	global_load_lds_dwordx4 v[218:219], off
	s_waitcnt vmcnt(8)
	s_waitcnt lgkmcnt(0)
	s_barrier
	s_setprio 1
	v_mfma_f32_16x16x32_bf16 v[126:129], v[130:133], v[162:165], v[126:129]
	v_mfma_f32_16x16x32_bf16 v[122:125], v[138:141], v[162:165], v[122:125]
	v_mfma_f32_16x16x32_bf16 v[110:113], v[130:133], v[170:173], v[110:113]
	v_mfma_f32_16x16x32_bf16 v[106:109], v[138:141], v[170:173], v[106:109]
	v_mfma_f32_16x16x32_bf16 v[94:97], v[130:133], v[194:197], v[94:97]
	v_mfma_f32_16x16x32_bf16 v[90:93], v[138:141], v[194:197], v[90:93]
	v_mfma_f32_16x16x32_bf16 v[78:81], v[130:133], v[202:205], v[78:81]
	v_mfma_f32_16x16x32_bf16 v[74:77], v[138:141], v[202:205], v[74:77]
	v_mfma_f32_16x16x32_bf16 v[126:129], v[134:137], v[166:169], v[126:129]
	v_mfma_f32_16x16x32_bf16 v[122:125], v[142:145], v[166:169], v[122:125]
	v_mfma_f32_16x16x32_bf16 v[110:113], v[134:137], v[174:177], v[110:113]
	v_mfma_f32_16x16x32_bf16 v[106:109], v[142:145], v[174:177], v[106:109]
	v_mfma_f32_16x16x32_bf16 v[94:97], v[134:137], v[198:201], v[94:97]
	v_mfma_f32_16x16x32_bf16 v[90:93], v[142:145], v[198:201], v[90:93]
	v_mfma_f32_16x16x32_bf16 v[78:81], v[134:137], v[214:217], v[78:81]
	v_mfma_f32_16x16x32_bf16 v[74:77], v[142:145], v[214:217], v[74:77]
	v_mfma_f32_16x16x32_bf16 v[118:121], v[146:149], v[162:165], v[118:121]
	v_mfma_f32_16x16x32_bf16 v[114:117], v[154:157], v[162:165], v[114:117]
	v_mfma_f32_16x16x32_bf16 v[102:105], v[146:149], v[170:173], v[102:105]
	v_mfma_f32_16x16x32_bf16 v[98:101], v[154:157], v[170:173], v[98:101]
	v_mfma_f32_16x16x32_bf16 v[86:89], v[146:149], v[194:197], v[86:89]
	v_mfma_f32_16x16x32_bf16 v[82:85], v[154:157], v[194:197], v[82:85]
	v_mfma_f32_16x16x32_bf16 v[70:73], v[146:149], v[202:205], v[70:73]
	v_mfma_f32_16x16x32_bf16 v[66:69], v[154:157], v[202:205], v[66:69]
	v_mfma_f32_16x16x32_bf16 v[118:121], v[150:153], v[166:169], v[118:121]
	v_mfma_f32_16x16x32_bf16 v[114:117], v[158:161], v[166:169], v[114:117]
	v_mfma_f32_16x16x32_bf16 v[102:105], v[150:153], v[174:177], v[102:105]
	v_mfma_f32_16x16x32_bf16 v[98:101], v[158:161], v[174:177], v[98:101]
	v_mfma_f32_16x16x32_bf16 v[86:89], v[150:153], v[198:201], v[86:89]
	v_mfma_f32_16x16x32_bf16 v[82:85], v[158:161], v[198:201], v[82:85]
	v_mfma_f32_16x16x32_bf16 v[70:73], v[150:153], v[214:217], v[70:73]
	v_mfma_f32_16x16x32_bf16 v[66:69], v[158:161], v[214:217], v[66:69]
	s_setprio 0
	s_barrier
	s_add_i32 s52, s41, s30
	v_lshl_add_u64 v[218:219], s[20:21], 0, v[180:181]
	s_mov_b32 m0, s52
	ds_read_b128 v[162:165], v209 offset:16384
	ds_read_b128 v[166:169], v209 offset:17408
	ds_read_b128 v[170:173], v209 offset:18432
	ds_read_b128 v[174:177], v209 offset:19456
	ds_read_b128 v[194:197], v209 offset:20480
	ds_read_b128 v[198:201], v209 offset:21504
	ds_read_b128 v[202:205], v209 offset:22528
	ds_read_b128 v[214:217], v209 offset:23552
	global_load_lds_dwordx4 v[218:219], off
	s_add_i32 m0, s52, 0x2000
	s_add_u32 s52, s20, 0xb0000
	v_lshl_add_u64 v[220:221], s[20:21], 0, v[184:185]
	s_addc_u32 s53, s21, 0
	s_add_i32 s54, s42, s30
	global_load_lds_dwordx4 v[220:221], off
	v_lshl_add_u64 v[222:223], s[52:53], 0, v[180:181]
	s_mov_b32 m0, s54
	v_lshl_add_u64 v[224:225], s[22:23], 0, v[182:183]
	global_load_lds_dwordx4 v[222:223], off
	v_lshl_add_u64 v[222:223], s[52:53], 0, v[184:185]
	s_add_i32 m0, s54, 0x2000
	s_nop 0
	global_load_lds_dwordx4 v[222:223], off
	v_lshl_add_u64 v[222:223], s[22:23], 0, v[178:179]
	s_mov_b32 m0, s31
	s_nop 0
	global_load_lds_dwordx4 v[222:223], off
	s_mov_b32 m0, s33
	s_nop 0
	global_load_lds_dwordx4 v[224:225], off
	s_waitcnt vmcnt(8)
	s_waitcnt lgkmcnt(0)
	s_barrier
	s_setprio 1
	v_mfma_f32_16x16x32_bf16 v[62:65], v[130:133], v[162:165], v[62:65]
	v_mfma_f32_16x16x32_bf16 v[58:61], v[138:141], v[162:165], v[58:61]
	v_mfma_f32_16x16x32_bf16 v[46:49], v[130:133], v[170:173], v[46:49]
	v_mfma_f32_16x16x32_bf16 v[42:45], v[138:141], v[170:173], v[42:45]
	v_mfma_f32_16x16x32_bf16 v[30:33], v[130:133], v[194:197], v[30:33]
	v_mfma_f32_16x16x32_bf16 v[26:29], v[138:141], v[194:197], v[26:29]
	v_mfma_f32_16x16x32_bf16 v[14:17], v[130:133], v[202:205], v[14:17]
	v_mfma_f32_16x16x32_bf16 v[10:13], v[138:141], v[202:205], v[10:13]
	v_mfma_f32_16x16x32_bf16 v[62:65], v[134:137], v[166:169], v[62:65]
	v_mfma_f32_16x16x32_bf16 v[58:61], v[142:145], v[166:169], v[58:61]
	v_mfma_f32_16x16x32_bf16 v[46:49], v[134:137], v[174:177], v[46:49]
	v_mfma_f32_16x16x32_bf16 v[42:45], v[142:145], v[174:177], v[42:45]
	v_mfma_f32_16x16x32_bf16 v[30:33], v[134:137], v[198:201], v[30:33]
	v_mfma_f32_16x16x32_bf16 v[26:29], v[142:145], v[198:201], v[26:29]
	v_mfma_f32_16x16x32_bf16 v[14:17], v[134:137], v[214:217], v[14:17]
	v_mfma_f32_16x16x32_bf16 v[10:13], v[142:145], v[214:217], v[10:13]
	v_mfma_f32_16x16x32_bf16 v[54:57], v[146:149], v[162:165], v[54:57]
	v_mfma_f32_16x16x32_bf16 v[50:53], v[154:157], v[162:165], v[50:53]
	v_mfma_f32_16x16x32_bf16 v[38:41], v[146:149], v[170:173], v[38:41]
	v_mfma_f32_16x16x32_bf16 v[34:37], v[154:157], v[170:173], v[34:37]
	v_mfma_f32_16x16x32_bf16 v[22:25], v[146:149], v[194:197], v[22:25]
	v_mfma_f32_16x16x32_bf16 v[18:21], v[154:157], v[194:197], v[18:21]
	v_mfma_f32_16x16x32_bf16 v[6:9], v[146:149], v[202:205], v[6:9]
	v_mfma_f32_16x16x32_bf16 v[2:5], v[154:157], v[202:205], v[2:5]
	v_mfma_f32_16x16x32_bf16 v[54:57], v[150:153], v[166:169], v[54:57]
	v_mfma_f32_16x16x32_bf16 v[50:53], v[158:161], v[166:169], v[50:53]
	v_mfma_f32_16x16x32_bf16 v[38:41], v[150:153], v[174:177], v[38:41]
	v_mfma_f32_16x16x32_bf16 v[34:37], v[158:161], v[174:177], v[34:37]
	v_mfma_f32_16x16x32_bf16 v[22:25], v[150:153], v[198:201], v[22:25]
	v_mfma_f32_16x16x32_bf16 v[18:21], v[158:161], v[198:201], v[18:21]
	v_mfma_f32_16x16x32_bf16 v[6:9], v[150:153], v[214:217], v[6:9]
	v_mfma_f32_16x16x32_bf16 v[2:5], v[158:161], v[214:217], v[2:5]
	s_setprio 0
	s_barrier
	ds_read_b128 v[130:133], v211
	ds_read_b128 v[134:137], v211 offset:1024
	ds_read_b128 v[138:141], v211 offset:2048
	ds_read_b128 v[142:145], v211 offset:3072
	ds_read_b128 v[146:149], v212
	ds_read_b128 v[150:153], v212 offset:1024
	ds_read_b128 v[154:157], v212 offset:2048
	ds_read_b128 v[158:161], v212 offset:3072
	s_add_u32 s22, s22, 0xb0000
	s_addc_u32 s23, s23, 0
	s_mov_b32 m0, s34
	v_lshl_add_u64 v[226:227], s[22:23], 0, v[178:179]
	ds_read_b128 v[162:165], v209 offset:32768
	ds_read_b128 v[166:169], v209 offset:33792
	ds_read_b128 v[170:173], v209 offset:34816
	ds_read_b128 v[174:177], v209 offset:35840
	ds_read_b128 v[194:197], v209 offset:36864
	ds_read_b128 v[198:201], v209 offset:37888
	ds_read_b128 v[202:205], v209 offset:38912
	ds_read_b128 v[214:217], v209 offset:39936
	global_load_lds_dwordx4 v[226:227], off
	v_lshl_add_u64 v[226:227], s[22:23], 0, v[182:183]
	s_mov_b32 m0, s35
	s_nop 0
	global_load_lds_dwordx4 v[226:227], off
	s_waitcnt vmcnt(8)
	s_waitcnt lgkmcnt(0)
	s_barrier
	s_setprio 1
	v_mfma_f32_16x16x32_bf16 v[126:129], v[130:133], v[162:165], v[126:129]
	v_mfma_f32_16x16x32_bf16 v[122:125], v[138:141], v[162:165], v[122:125]
	v_mfma_f32_16x16x32_bf16 v[110:113], v[130:133], v[170:173], v[110:113]
	v_mfma_f32_16x16x32_bf16 v[106:109], v[138:141], v[170:173], v[106:109]
	v_mfma_f32_16x16x32_bf16 v[94:97], v[130:133], v[194:197], v[94:97]
	v_mfma_f32_16x16x32_bf16 v[90:93], v[138:141], v[194:197], v[90:93]
	v_mfma_f32_16x16x32_bf16 v[78:81], v[130:133], v[202:205], v[78:81]
	v_mfma_f32_16x16x32_bf16 v[74:77], v[138:141], v[202:205], v[74:77]
	v_mfma_f32_16x16x32_bf16 v[126:129], v[134:137], v[166:169], v[126:129]
	v_mfma_f32_16x16x32_bf16 v[122:125], v[142:145], v[166:169], v[122:125]
	v_mfma_f32_16x16x32_bf16 v[110:113], v[134:137], v[174:177], v[110:113]
	v_mfma_f32_16x16x32_bf16 v[106:109], v[142:145], v[174:177], v[106:109]
	v_mfma_f32_16x16x32_bf16 v[94:97], v[134:137], v[198:201], v[94:97]
	v_mfma_f32_16x16x32_bf16 v[90:93], v[142:145], v[198:201], v[90:93]
	v_mfma_f32_16x16x32_bf16 v[78:81], v[134:137], v[214:217], v[78:81]
	v_mfma_f32_16x16x32_bf16 v[74:77], v[142:145], v[214:217], v[74:77]
	v_mfma_f32_16x16x32_bf16 v[118:121], v[146:149], v[162:165], v[118:121]
	v_mfma_f32_16x16x32_bf16 v[114:117], v[154:157], v[162:165], v[114:117]
	v_mfma_f32_16x16x32_bf16 v[102:105], v[146:149], v[170:173], v[102:105]
	v_mfma_f32_16x16x32_bf16 v[98:101], v[154:157], v[170:173], v[98:101]
	v_mfma_f32_16x16x32_bf16 v[86:89], v[146:149], v[194:197], v[86:89]
	v_mfma_f32_16x16x32_bf16 v[82:85], v[154:157], v[194:197], v[82:85]
	v_mfma_f32_16x16x32_bf16 v[70:73], v[146:149], v[202:205], v[70:73]
	v_mfma_f32_16x16x32_bf16 v[66:69], v[154:157], v[202:205], v[66:69]
	v_mfma_f32_16x16x32_bf16 v[118:121], v[150:153], v[166:169], v[118:121]
	v_mfma_f32_16x16x32_bf16 v[114:117], v[158:161], v[166:169], v[114:117]
	v_mfma_f32_16x16x32_bf16 v[102:105], v[150:153], v[174:177], v[102:105]
	v_mfma_f32_16x16x32_bf16 v[98:101], v[158:161], v[174:177], v[98:101]
	v_mfma_f32_16x16x32_bf16 v[86:89], v[150:153], v[198:201], v[86:89]
	v_mfma_f32_16x16x32_bf16 v[82:85], v[158:161], v[198:201], v[82:85]
	v_mfma_f32_16x16x32_bf16 v[70:73], v[150:153], v[214:217], v[70:73]
	v_mfma_f32_16x16x32_bf16 v[66:69], v[158:161], v[214:217], v[66:69]
	s_setprio 0
	s_barrier
	s_add_i32 s22, s43, s30
	v_lshl_add_u64 v[218:219], v[218:219], 0, s[14:15]
	s_mov_b32 m0, s22
	ds_read_b128 v[162:165], v209 offset:49152
	ds_read_b128 v[166:169], v209 offset:50176
	ds_read_b128 v[170:173], v209 offset:51200
	ds_read_b128 v[174:177], v209 offset:52224
	ds_read_b128 v[194:197], v209 offset:53248
	ds_read_b128 v[198:201], v209 offset:54272
	ds_read_b128 v[202:205], v209 offset:55296
	ds_read_b128 v[214:217], v209 offset:56320
	global_load_lds_dwordx4 v[218:219], off
	s_add_i32 m0, s22, 0x2000
	s_add_u32 s20, s20, 0xb0080
	v_lshl_add_u64 v[218:219], v[220:221], 0, s[14:15]
	s_addc_u32 s21, s21, 0
	s_add_i32 s22, s44, s30
	global_load_lds_dwordx4 v[218:219], off
	v_lshl_add_u64 v[218:219], s[20:21], 0, v[180:181]
	s_mov_b32 m0, s22
	s_nop 0
	global_load_lds_dwordx4 v[218:219], off
	v_lshl_add_u64 v[218:219], s[20:21], 0, v[184:185]
	s_add_i32 m0, s22, 0x2000
	s_nop 0
	global_load_lds_dwordx4 v[218:219], off
	v_lshl_add_u64 v[218:219], v[222:223], 0, s[14:15]
	s_mov_b32 m0, s37
	s_nop 0
	global_load_lds_dwordx4 v[218:219], off
	v_lshl_add_u64 v[218:219], v[224:225], 0, s[14:15]
	s_mov_b32 m0, s38
	s_nop 0
	global_load_lds_dwordx4 v[218:219], off
	s_waitcnt vmcnt(8)
	s_waitcnt lgkmcnt(0)
	s_barrier
	s_setprio 1
	v_mfma_f32_16x16x32_bf16 v[62:65], v[130:133], v[162:165], v[62:65]
	v_mfma_f32_16x16x32_bf16 v[58:61], v[138:141], v[162:165], v[58:61]
	v_mfma_f32_16x16x32_bf16 v[46:49], v[130:133], v[170:173], v[46:49]
	v_mfma_f32_16x16x32_bf16 v[42:45], v[138:141], v[170:173], v[42:45]
	v_mfma_f32_16x16x32_bf16 v[30:33], v[130:133], v[194:197], v[30:33]
	v_mfma_f32_16x16x32_bf16 v[26:29], v[138:141], v[194:197], v[26:29]
	v_mfma_f32_16x16x32_bf16 v[14:17], v[130:133], v[202:205], v[14:17]
	v_mfma_f32_16x16x32_bf16 v[10:13], v[138:141], v[202:205], v[10:13]
	v_mfma_f32_16x16x32_bf16 v[62:65], v[134:137], v[166:169], v[62:65]
	v_mfma_f32_16x16x32_bf16 v[58:61], v[142:145], v[166:169], v[58:61]
	v_mfma_f32_16x16x32_bf16 v[46:49], v[134:137], v[174:177], v[46:49]
	v_mfma_f32_16x16x32_bf16 v[42:45], v[142:145], v[174:177], v[42:45]
	v_mfma_f32_16x16x32_bf16 v[30:33], v[134:137], v[198:201], v[30:33]
	v_mfma_f32_16x16x32_bf16 v[26:29], v[142:145], v[198:201], v[26:29]
	v_mfma_f32_16x16x32_bf16 v[14:17], v[134:137], v[214:217], v[14:17]
	v_mfma_f32_16x16x32_bf16 v[10:13], v[142:145], v[214:217], v[10:13]
	v_mfma_f32_16x16x32_bf16 v[54:57], v[146:149], v[162:165], v[54:57]
	v_mfma_f32_16x16x32_bf16 v[50:53], v[154:157], v[162:165], v[50:53]
	v_mfma_f32_16x16x32_bf16 v[38:41], v[146:149], v[170:173], v[38:41]
	v_mfma_f32_16x16x32_bf16 v[34:37], v[154:157], v[170:173], v[34:37]
	v_mfma_f32_16x16x32_bf16 v[22:25], v[146:149], v[194:197], v[22:25]
	v_mfma_f32_16x16x32_bf16 v[18:21], v[154:157], v[194:197], v[18:21]
	v_mfma_f32_16x16x32_bf16 v[6:9], v[146:149], v[202:205], v[6:9]
	v_mfma_f32_16x16x32_bf16 v[2:5], v[154:157], v[202:205], v[2:5]
	v_mfma_f32_16x16x32_bf16 v[54:57], v[150:153], v[166:169], v[54:57]
	v_mfma_f32_16x16x32_bf16 v[50:53], v[158:161], v[166:169], v[50:53]
	v_mfma_f32_16x16x32_bf16 v[38:41], v[150:153], v[174:177], v[38:41]
	v_mfma_f32_16x16x32_bf16 v[34:37], v[158:161], v[174:177], v[34:37]
	v_mfma_f32_16x16x32_bf16 v[22:25], v[150:153], v[198:201], v[22:25]
	v_mfma_f32_16x16x32_bf16 v[18:21], v[158:161], v[198:201], v[18:21]
	v_mfma_f32_16x16x32_bf16 v[6:9], v[150:153], v[214:217], v[6:9]
	v_mfma_f32_16x16x32_bf16 v[2:5], v[158:161], v[214:217], v[2:5]
	s_setprio 0
	s_barrier
	s_add_i32 s51, s51, 2
	s_add_u32 s18, s18, 0x100
	s_addc_u32 s19, s19, 0
	s_add_u32 s49, s49, 0x100
	s_addc_u32 s50, s50, 0
	s_cmp_gt_u32 s51, 41
	s_cbranch_scc0 .LBB0_294
	s_load_dwordx16 s[80:95], s[76:77], 0x0
	v_lshl_add_u32 v198, s48, 8, v1
	v_lshl_or_b32 v194, s16, 8, v206
	v_ashrrev_i32_e32 v195, 31, v194
	v_ashrrev_i32_e32 v199, 31, v198
	s_waitcnt lgkmcnt(0)
	v_lshl_add_u64 v[196:197], v[194:195], 2, s[80:81]
	v_lshlrev_b64 v[130:131], 12, v[198:199]
	v_lshl_add_u64 v[130:131], v[196:197], 0, v[130:131]
	global_load_dwordx4 v[214:217], v[130:131], off nt
	global_load_dwordx4 v[218:221], v[130:131], off offset:16 nt
	global_load_dwordx4 v[222:225], v[130:131], off offset:512 nt
	global_load_dwordx4 v[226:229], v[130:131], off offset:528 nt
	v_or_b32_e32 v204, 16, v198
	v_or_b32_e32 v202, 32, v198
	v_or_b32_e32 v200, 48, v198
	v_ashrrev_i32_e32 v205, 31, v204
	v_ashrrev_i32_e32 v203, 31, v202
	v_ashrrev_i32_e32 v201, 31, v200
	v_lshlrev_b64 v[130:131], 12, v[204:205]
	v_lshlrev_b64 v[132:133], 12, v[202:203]
	v_lshlrev_b64 v[134:135], 12, v[200:201]
	v_lshl_add_u64 v[130:131], v[196:197], 0, v[130:131]
	v_lshl_add_u64 v[132:133], v[196:197], 0, v[132:133]
	v_lshl_add_u64 v[134:135], v[196:197], 0, v[134:135]
	global_load_dwordx4 v[170:173], v[130:131], off offset:16 nt
	global_load_dwordx4 v[174:177], v[130:131], off nt
	global_load_dwordx4 v[162:165], v[130:131], off offset:528 nt
	global_load_dwordx4 v[166:169], v[130:131], off offset:512 nt
	global_load_dwordx4 v[154:157], v[132:133], off offset:16 nt
	global_load_dwordx4 v[158:161], v[132:133], off nt
	global_load_dwordx4 v[146:149], v[132:133], off offset:528 nt
	global_load_dwordx4 v[150:153], v[132:133], off offset:512 nt
	global_load_dwordx4 v[138:141], v[134:135], off offset:16 nt
	global_load_dwordx4 v[142:145], v[134:135], off nt
	s_nop 0
	global_load_dwordx4 v[130:133], v[134:135], off offset:528 nt
	s_nop 0
	global_load_dwordx4 v[134:137], v[134:135], off offset:512 nt
	v_and_b32_e32 v230, 64, v210
	v_xor_b32_e32 v213, 16, v210
	v_add_u32_e32 v233, 64, v230
	v_xor_b32_e32 v232, 32, v210
	v_lshlrev_b64 v[230:231], 10, v[198:199]
	v_cmp_lt_i32_e32 vcc, v213, v233
	v_lshl_add_u64 v[230:231], v[230:231], 0, v[194:195]
	s_lshl_b32 s18, s16, 2
	v_cndmask_b32_e32 v213, v210, v213, vcc
	v_cmp_lt_i32_e32 vcc, v232, v233
	v_lshlrev_b32_e32 v213, 2, v213
	s_ashr_i32 s19, s18, 31
	v_cndmask_b32_e32 v236, v210, v232, vcc
	v_lshl_add_u64 v[232:233], v[230:231], 2, s[62:63]
	v_lshlrev_b64 v[230:231], 1, v[230:231]
	v_lshl_add_u64 v[234:235], s[2:3], 0, v[230:231]
	v_or_b32_e32 v230, 0x100, v230
	s_waitcnt vmcnt(0)
	v_pk_fma_f32 v[128:129], v[128:129], 0.5, v[216:217] op_sel_hi:[1,0,1]
	v_pk_fma_f32 v[126:127], v[126:127], 0.5, v[214:215] op_sel_hi:[1,0,1]
	v_pk_fma_f32 v[120:121], v[120:121], 0.5, v[224:225] op_sel_hi:[1,0,1]
	v_pk_fma_f32 v[118:119], v[118:119], 0.5, v[222:223] op_sel_hi:[1,0,1]
	v_pk_fma_f32 v[124:125], v[124:125], 0.5, v[220:221] op_sel_hi:[1,0,1]
	v_pk_fma_f32 v[122:123], v[122:123], 0.5, v[218:219] op_sel_hi:[1,0,1]
	v_pk_fma_f32 v[114:115], v[114:115], 0.5, v[226:227] op_sel_hi:[1,0,1]
	global_store_dwordx4 v[232:233], v[126:129], off nt
	global_store_dwordx4 v[232:233], v[122:125], off offset:16 nt
	v_cvt_pk_bf16_f32 v214, v126, v127
	v_cvt_pk_bf16_f32 v215, v128, v129
	v_mul_f32_e32 v218, v119, v119
	v_mul_f32_e32 v127, v127, v127
	v_mul_f32_e32 v129, v129, v129
	v_mul_f32_e32 v219, v121, v121
	v_pk_fma_f32 v[116:117], v[116:117], 0.5, v[228:229] op_sel_hi:[1,0,1]
	v_cvt_pk_bf16_f32 v216, v122, v123
	v_cvt_pk_bf16_f32 v217, v124, v125
	v_mul_f32_e32 v123, v123, v123
	v_mul_f32_e32 v125, v125, v125
	v_mul_f32_e32 v220, v115, v115
	v_fmac_f32_e32 v127, v126, v126
	v_fmac_f32_e32 v129, v128, v128
	v_fmac_f32_e32 v218, v118, v118
	v_fmac_f32_e32 v219, v120, v120
	v_mul_f32_e32 v221, v117, v117
	v_fmac_f32_e32 v123, v122, v122
	v_fmac_f32_e32 v125, v124, v124
	v_fmac_f32_e32 v220, v114, v114
	v_add_f32_e32 v122, v127, v129
	v_add_f32_e32 v124, v218, v219
	v_fmac_f32_e32 v221, v116, v116
	v_add_f32_e32 v122, v122, v123
	v_add_f32_e32 v123, v124, v220
	v_add_f32_e32 v122, v125, v122
	v_add_f32_e32 v123, v221, v123
	v_add_f32_e32 v122, v122, v123
	ds_bpermute_b32 v123, v213, v122
	global_store_dwordx4 v[234:235], v[214:217], off
	global_store_dwordx4 v[232:233], v[118:121], off offset:512 nt
	global_store_dwordx4 v[232:233], v[114:117], off offset:528 nt
	s_nop 0
	v_cvt_pk_bf16_f32 v118, v118, v119
	v_cvt_pk_bf16_f32 v119, v120, v121
	v_cvt_pk_bf16_f32 v120, v114, v115
	v_cvt_pk_bf16_f32 v121, v116, v117
	s_waitcnt lgkmcnt(0)
	v_add_f32_e32 v114, v122, v123
	v_lshlrev_b32_e32 v122, 2, v236
	ds_bpermute_b32 v115, v122, v114
	v_lshl_add_u64 v[116:117], s[2:3], 0, v[230:231]
	global_store_dwordx4 v[116:117], v[118:121], off
	s_and_saveexec_b64 s[20:21], s[4:5]
	s_cbranch_execz .LBB0_297
	s_waitcnt lgkmcnt(0)
	v_add_f32_e32 v116, v114, v115
	v_lshlrev_b64 v[114:115], 6, v[198:199]
	v_lshl_add_u64 v[114:115], s[12:13], 0, v[114:115]
	v_lshl_add_u64 v[114:115], s[18:19], 2, v[114:115]
	s_lshl_b32 s16, s36, 2
	v_lshl_add_u64 v[114:115], v[114:115], 0, s[16:17]
	global_store_dword v[114:115], v116, off

.LBB0_338:
	ds_read_b128 v[82:85], v165
	ds_read_b128 v[86:89], v165 offset:1024
	ds_read_b128 v[90:93], v165 offset:2048
	ds_read_b128 v[94:97], v165 offset:3072
	ds_read_b128 v[146:149], v184
	ds_read_b128 v[150:153], v184 offset:1024
	ds_read_b128 v[180:183], v184 offset:2048
	ds_read_b128 v[194:197], v184 offset:3072
	s_add_u32 s12, s10, 0xfffc0080
	s_addc_u32 s13, s11, -1
	s_cmp_eq_u32 s72, 12
	s_cselect_b32 s15, s1, s13
	s_cselect_b32 s14, s3, s12
	s_cselect_b32 s13, s16, s35
	s_cselect_b32 s12, s17, s31
	v_lshl_add_u64 v[230:231], s[10:11], 0, v[170:171]
	s_add_i32 m0, s44, 0xc000
	ds_read_b128 v[198:201], v185
	ds_read_b128 v[202:205], v185 offset:1024
	ds_read_b128 v[206:209], v185 offset:2048
	ds_read_b128 v[210:213], v185 offset:3072
	ds_read_b128 v[214:217], v185 offset:4096
	ds_read_b128 v[218:221], v185 offset:5120
	ds_read_b128 v[222:225], v185 offset:6144
	ds_read_b128 v[226:229], v185 offset:7168
	global_load_lds_dwordx4 v[230:231], off
	v_lshl_add_u64 v[230:231], s[10:11], 0, v[172:173]
	s_add_i32 m0, s44, 0xe000
	s_nop 0
	global_load_lds_dwordx4 v[230:231], off
	s_waitcnt vmcnt(8)
	s_waitcnt lgkmcnt(0)
	s_barrier
	s_setprio 1
	v_mfma_f32_16x16x32_bf16 v[62:65], v[82:85], v[198:201], v[62:65]
	v_mfma_f32_16x16x32_bf16 v[58:61], v[90:93], v[198:201], v[58:61]
	v_mfma_f32_16x16x32_bf16 v[54:57], v[82:85], v[206:209], v[54:57]
	v_mfma_f32_16x16x32_bf16 v[50:53], v[90:93], v[206:209], v[50:53]
	v_mfma_f32_16x16x32_bf16 v[46:49], v[82:85], v[214:217], v[46:49]
	v_mfma_f32_16x16x32_bf16 v[42:45], v[90:93], v[214:217], v[42:45]
	v_mfma_f32_16x16x32_bf16 v[38:41], v[82:85], v[222:225], v[38:41]
	v_mfma_f32_16x16x32_bf16 v[34:37], v[90:93], v[222:225], v[34:37]
	v_mfma_f32_16x16x32_bf16 v[62:65], v[86:89], v[202:205], v[62:65]
	v_mfma_f32_16x16x32_bf16 v[58:61], v[94:97], v[202:205], v[58:61]
	v_mfma_f32_16x16x32_bf16 v[54:57], v[86:89], v[210:213], v[54:57]
	v_mfma_f32_16x16x32_bf16 v[50:53], v[94:97], v[210:213], v[50:53]
	v_mfma_f32_16x16x32_bf16 v[46:49], v[86:89], v[218:221], v[46:49]
	v_mfma_f32_16x16x32_bf16 v[42:45], v[94:97], v[218:221], v[42:45]
	v_mfma_f32_16x16x32_bf16 v[38:41], v[86:89], v[226:229], v[38:41]
	v_mfma_f32_16x16x32_bf16 v[34:37], v[94:97], v[226:229], v[34:37]
	v_mfma_f32_16x16x32_bf16 v[142:145], v[146:149], v[198:201], v[142:145]
	v_mfma_f32_16x16x32_bf16 v[138:141], v[180:183], v[198:201], v[138:141]
	v_mfma_f32_16x16x32_bf16 v[134:137], v[146:149], v[206:209], v[134:137]
	v_mfma_f32_16x16x32_bf16 v[130:133], v[180:183], v[206:209], v[130:133]
	v_mfma_f32_16x16x32_bf16 v[126:129], v[146:149], v[214:217], v[126:129]
	v_mfma_f32_16x16x32_bf16 v[122:125], v[180:183], v[214:217], v[122:125]
	v_mfma_f32_16x16x32_bf16 v[118:121], v[146:149], v[222:225], v[118:121]
	v_mfma_f32_16x16x32_bf16 v[114:117], v[180:183], v[222:225], v[114:117]
	v_mfma_f32_16x16x32_bf16 v[142:145], v[150:153], v[202:205], v[142:145]
	v_mfma_f32_16x16x32_bf16 v[138:141], v[194:197], v[202:205], v[138:141]
	v_mfma_f32_16x16x32_bf16 v[134:137], v[150:153], v[210:213], v[134:137]
	v_mfma_f32_16x16x32_bf16 v[130:133], v[194:197], v[210:213], v[130:133]
	v_mfma_f32_16x16x32_bf16 v[126:129], v[150:153], v[218:221], v[126:129]
	v_mfma_f32_16x16x32_bf16 v[122:125], v[194:197], v[218:221], v[122:125]
	v_mfma_f32_16x16x32_bf16 v[118:121], v[150:153], v[226:229], v[118:121]
	v_mfma_f32_16x16x32_bf16 v[114:117], v[194:197], v[226:229], v[114:117]
	s_setprio 0
	s_barrier
	s_add_i32 s73, s56, s43
	v_lshl_add_u64 v[230:231], s[12:13], 0, v[156:157]
	s_mov_b32 m0, s73
	ds_read_b128 v[198:201], v185 offset:16384
	ds_read_b128 v[202:205], v185 offset:17408
	ds_read_b128 v[206:209], v185 offset:18432
	ds_read_b128 v[210:213], v185 offset:19456
	ds_read_b128 v[214:217], v185 offset:20480
	ds_read_b128 v[218:221], v185 offset:21504
	ds_read_b128 v[222:225], v185 offset:22528
	ds_read_b128 v[226:229], v185 offset:23552
	global_load_lds_dwordx4 v[230:231], off
	s_add_i32 m0, s73, 0x2000
	s_add_u32 s74, s12, 0x40000
	v_lshl_add_u64 v[232:233], s[12:13], 0, v[160:161]
	s_addc_u32 s75, s13, 0
	s_add_i32 s73, s57, s43
	global_load_lds_dwordx4 v[232:233], off
	v_lshl_add_u64 v[234:235], s[74:75], 0, v[156:157]
	s_mov_b32 m0, s73
	v_lshl_add_u64 v[236:237], s[14:15], 0, v[158:159]
	global_load_lds_dwordx4 v[234:235], off
	v_lshl_add_u64 v[234:235], s[74:75], 0, v[160:161]
	s_add_i32 m0, s73, 0x2000
	s_nop 0
	global_load_lds_dwordx4 v[234:235], off
	v_lshl_add_u64 v[234:235], s[14:15], 0, v[154:155]
	s_mov_b32 m0, s44
	s_nop 0
	global_load_lds_dwordx4 v[234:235], off
	s_mov_b32 m0, s45
	s_nop 0
	global_load_lds_dwordx4 v[236:237], off
	s_waitcnt vmcnt(8)
	s_waitcnt lgkmcnt(0)
	s_barrier
	s_setprio 1
	v_mfma_f32_16x16x32_bf16 v[30:33], v[82:85], v[198:201], v[30:33]
	v_mfma_f32_16x16x32_bf16 v[26:29], v[90:93], v[198:201], v[26:29]
	v_mfma_f32_16x16x32_bf16 v[22:25], v[82:85], v[206:209], v[22:25]
	v_mfma_f32_16x16x32_bf16 v[18:21], v[90:93], v[206:209], v[18:21]
	v_mfma_f32_16x16x32_bf16 v[14:17], v[82:85], v[214:217], v[14:17]
	v_mfma_f32_16x16x32_bf16 v[10:13], v[90:93], v[214:217], v[10:13]
	v_mfma_f32_16x16x32_bf16 v[6:9], v[82:85], v[222:225], v[6:9]
	v_mfma_f32_16x16x32_bf16 v[2:5], v[90:93], v[222:225], v[2:5]
	v_mfma_f32_16x16x32_bf16 v[30:33], v[86:89], v[202:205], v[30:33]
	v_mfma_f32_16x16x32_bf16 v[26:29], v[94:97], v[202:205], v[26:29]
	v_mfma_f32_16x16x32_bf16 v[22:25], v[86:89], v[210:213], v[22:25]
	v_mfma_f32_16x16x32_bf16 v[18:21], v[94:97], v[210:213], v[18:21]
	v_mfma_f32_16x16x32_bf16 v[14:17], v[86:89], v[218:221], v[14:17]
	v_mfma_f32_16x16x32_bf16 v[10:13], v[94:97], v[218:221], v[10:13]
	v_mfma_f32_16x16x32_bf16 v[6:9], v[86:89], v[226:229], v[6:9]
	v_mfma_f32_16x16x32_bf16 v[2:5], v[94:97], v[226:229], v[2:5]
	v_mfma_f32_16x16x32_bf16 v[78:81], v[146:149], v[214:217], v[78:81]
	v_mfma_f32_16x16x32_bf16 v[74:77], v[180:183], v[214:217], v[74:77]
	v_mfma_f32_16x16x32_bf16 v[70:73], v[146:149], v[222:225], v[70:73]
	v_mfma_f32_16x16x32_bf16 v[66:69], v[180:183], v[222:225], v[66:69]
	v_mfma_f32_16x16x32_bf16 v[82:85], v[146:149], v[198:201], v[110:113]
	v_mfma_f32_16x16x32_bf16 v[86:89], v[180:183], v[198:201], v[106:109]
	v_mfma_f32_16x16x32_bf16 v[90:93], v[146:149], v[206:209], v[102:105]
	v_mfma_f32_16x16x32_bf16 v[94:97], v[180:183], v[206:209], v[98:101]
	v_mfma_f32_16x16x32_bf16 v[78:81], v[150:153], v[218:221], v[78:81]
	v_mfma_f32_16x16x32_bf16 v[74:77], v[194:197], v[218:221], v[74:77]
	v_mfma_f32_16x16x32_bf16 v[70:73], v[150:153], v[226:229], v[70:73]
	v_mfma_f32_16x16x32_bf16 v[66:69], v[194:197], v[226:229], v[66:69]
	v_mfma_f32_16x16x32_bf16 v[82:85], v[150:153], v[202:205], v[82:85]
	v_mfma_f32_16x16x32_bf16 v[86:89], v[194:197], v[202:205], v[86:89]
	v_mfma_f32_16x16x32_bf16 v[90:93], v[150:153], v[210:213], v[90:93]
	v_mfma_f32_16x16x32_bf16 v[94:97], v[194:197], v[210:213], v[94:97]
	s_setprio 0
	s_barrier
	ds_read_b128 v[98:101], v189
	ds_read_b128 v[102:105], v189 offset:1024
	ds_read_b128 v[106:109], v189 offset:2048
	ds_read_b128 v[110:113], v189 offset:3072
	ds_read_b128 v[146:149], v190
	ds_read_b128 v[150:153], v190 offset:1024
	ds_read_b128 v[180:183], v190 offset:2048
	ds_read_b128 v[194:197], v190 offset:3072
	s_add_u32 s14, s14, 0x40000
	s_addc_u32 s15, s15, 0
	s_mov_b32 m0, s46
	v_lshl_add_u64 v[238:239], s[14:15], 0, v[154:155]
	ds_read_b128 v[198:201], v185 offset:32768
	ds_read_b128 v[202:205], v185 offset:33792
	ds_read_b128 v[206:209], v185 offset:34816
	ds_read_b128 v[210:213], v185 offset:35840
	ds_read_b128 v[214:217], v185 offset:36864
	ds_read_b128 v[218:221], v185 offset:37888
	ds_read_b128 v[222:225], v185 offset:38912
	ds_read_b128 v[226:229], v185 offset:39936
	global_load_lds_dwordx4 v[238:239], off
	v_lshl_add_u64 v[238:239], s[14:15], 0, v[158:159]
	s_mov_b32 m0, s47
	s_nop 0
	global_load_lds_dwordx4 v[238:239], off
	s_waitcnt vmcnt(8)
	s_waitcnt lgkmcnt(0)
	s_barrier
	s_setprio 1
	v_mfma_f32_16x16x32_bf16 v[62:65], v[98:101], v[198:201], v[62:65]
	v_mfma_f32_16x16x32_bf16 v[58:61], v[106:109], v[198:201], v[58:61]
	v_mfma_f32_16x16x32_bf16 v[54:57], v[98:101], v[206:209], v[54:57]
	v_mfma_f32_16x16x32_bf16 v[50:53], v[106:109], v[206:209], v[50:53]
	v_mfma_f32_16x16x32_bf16 v[46:49], v[98:101], v[214:217], v[46:49]
	v_mfma_f32_16x16x32_bf16 v[42:45], v[106:109], v[214:217], v[42:45]
	v_mfma_f32_16x16x32_bf16 v[38:41], v[98:101], v[222:225], v[38:41]
	v_mfma_f32_16x16x32_bf16 v[34:37], v[106:109], v[222:225], v[34:37]
	v_mfma_f32_16x16x32_bf16 v[62:65], v[102:105], v[202:205], v[62:65]
	v_mfma_f32_16x16x32_bf16 v[58:61], v[110:113], v[202:205], v[58:61]
	v_mfma_f32_16x16x32_bf16 v[54:57], v[102:105], v[210:213], v[54:57]
	v_mfma_f32_16x16x32_bf16 v[50:53], v[110:113], v[210:213], v[50:53]
	v_mfma_f32_16x16x32_bf16 v[46:49], v[102:105], v[218:221], v[46:49]
	v_mfma_f32_16x16x32_bf16 v[42:45], v[110:113], v[218:221], v[42:45]
	v_mfma_f32_16x16x32_bf16 v[38:41], v[102:105], v[226:229], v[38:41]
	v_mfma_f32_16x16x32_bf16 v[34:37], v[110:113], v[226:229], v[34:37]
	v_mfma_f32_16x16x32_bf16 v[142:145], v[146:149], v[198:201], v[142:145]
	v_mfma_f32_16x16x32_bf16 v[138:141], v[180:183], v[198:201], v[138:141]
	v_mfma_f32_16x16x32_bf16 v[134:137], v[146:149], v[206:209], v[134:137]
	v_mfma_f32_16x16x32_bf16 v[130:133], v[180:183], v[206:209], v[130:133]
	v_mfma_f32_16x16x32_bf16 v[126:129], v[146:149], v[214:217], v[126:129]
	v_mfma_f32_16x16x32_bf16 v[122:125], v[180:183], v[214:217], v[122:125]
	v_mfma_f32_16x16x32_bf16 v[118:121], v[146:149], v[222:225], v[118:121]
	v_mfma_f32_16x16x32_bf16 v[114:117], v[180:183], v[222:225], v[114:117]
	v_mfma_f32_16x16x32_bf16 v[142:145], v[150:153], v[202:205], v[142:145]
	v_mfma_f32_16x16x32_bf16 v[138:141], v[194:197], v[202:205], v[138:141]
	v_mfma_f32_16x16x32_bf16 v[134:137], v[150:153], v[210:213], v[134:137]
	v_mfma_f32_16x16x32_bf16 v[130:133], v[194:197], v[210:213], v[130:133]
	v_mfma_f32_16x16x32_bf16 v[126:129], v[150:153], v[218:221], v[126:129]
	v_mfma_f32_16x16x32_bf16 v[122:125], v[194:197], v[218:221], v[122:125]
	v_mfma_f32_16x16x32_bf16 v[118:121], v[150:153], v[226:229], v[118:121]
	v_mfma_f32_16x16x32_bf16 v[114:117], v[194:197], v[226:229], v[114:117]
	s_setprio 0
	s_barrier
	s_add_i32 s14, s70, s43
	v_lshl_add_u64 v[230:231], v[230:231], 0, s[26:27]
	s_mov_b32 m0, s14
	ds_read_b128 v[198:201], v185 offset:49152
	ds_read_b128 v[202:205], v185 offset:50176
	ds_read_b128 v[206:209], v185 offset:51200
	ds_read_b128 v[210:213], v185 offset:52224
	ds_read_b128 v[214:217], v185 offset:53248
	ds_read_b128 v[218:221], v185 offset:54272
	ds_read_b128 v[222:225], v185 offset:55296
	ds_read_b128 v[226:229], v185 offset:56320
	global_load_lds_dwordx4 v[230:231], off
	s_add_i32 m0, s14, 0x2000
	s_add_u32 s12, s12, 0x40080
	v_lshl_add_u64 v[230:231], v[232:233], 0, s[26:27]
	s_addc_u32 s13, s13, 0
	s_add_i32 s14, s71, s43
	global_load_lds_dwordx4 v[230:231], off
	v_lshl_add_u64 v[230:231], s[12:13], 0, v[156:157]
	s_mov_b32 m0, s14
	s_nop 0
	global_load_lds_dwordx4 v[230:231], off
	v_lshl_add_u64 v[230:231], s[12:13], 0, v[160:161]
	s_add_i32 m0, s14, 0x2000
	s_nop 0
	global_load_lds_dwordx4 v[230:231], off
	v_lshl_add_u64 v[230:231], v[234:235], 0, s[26:27]
	s_mov_b32 m0, s50
	s_nop 0
	global_load_lds_dwordx4 v[230:231], off
	v_lshl_add_u64 v[230:231], v[236:237], 0, s[26:27]
	s_mov_b32 m0, s51
	s_nop 0
	global_load_lds_dwordx4 v[230:231], off
	s_waitcnt vmcnt(8)
	s_waitcnt lgkmcnt(0)
	s_barrier
	s_setprio 1
	v_mfma_f32_16x16x32_bf16 v[30:33], v[98:101], v[198:201], v[30:33]
	v_mfma_f32_16x16x32_bf16 v[26:29], v[106:109], v[198:201], v[26:29]
	v_mfma_f32_16x16x32_bf16 v[22:25], v[98:101], v[206:209], v[22:25]
	v_mfma_f32_16x16x32_bf16 v[18:21], v[106:109], v[206:209], v[18:21]
	v_mfma_f32_16x16x32_bf16 v[14:17], v[98:101], v[214:217], v[14:17]
	v_mfma_f32_16x16x32_bf16 v[10:13], v[106:109], v[214:217], v[10:13]
	v_mfma_f32_16x16x32_bf16 v[6:9], v[98:101], v[222:225], v[6:9]
	v_mfma_f32_16x16x32_bf16 v[2:5], v[106:109], v[222:225], v[2:5]
	v_mfma_f32_16x16x32_bf16 v[30:33], v[102:105], v[202:205], v[30:33]
	v_mfma_f32_16x16x32_bf16 v[26:29], v[110:113], v[202:205], v[26:29]
	v_mfma_f32_16x16x32_bf16 v[22:25], v[102:105], v[210:213], v[22:25]
	v_mfma_f32_16x16x32_bf16 v[18:21], v[110:113], v[210:213], v[18:21]
	v_mfma_f32_16x16x32_bf16 v[14:17], v[102:105], v[218:221], v[14:17]
	v_mfma_f32_16x16x32_bf16 v[10:13], v[110:113], v[218:221], v[10:13]
	v_mfma_f32_16x16x32_bf16 v[6:9], v[102:105], v[226:229], v[6:9]
	v_mfma_f32_16x16x32_bf16 v[2:5], v[110:113], v[226:229], v[2:5]
	v_mfma_f32_16x16x32_bf16 v[82:85], v[146:149], v[198:201], v[82:85]
	v_mfma_f32_16x16x32_bf16 v[110:113], v[150:153], v[202:205], v[82:85]
	v_mfma_f32_16x16x32_bf16 v[82:85], v[180:183], v[198:201], v[86:89]
	v_mfma_f32_16x16x32_bf16 v[106:109], v[194:197], v[202:205], v[82:85]
	v_mfma_f32_16x16x32_bf16 v[82:85], v[146:149], v[206:209], v[90:93]
	v_mfma_f32_16x16x32_bf16 v[102:105], v[150:153], v[210:213], v[82:85]
	v_mfma_f32_16x16x32_bf16 v[82:85], v[180:183], v[206:209], v[94:97]
	v_mfma_f32_16x16x32_bf16 v[78:81], v[146:149], v[214:217], v[78:81]
	v_mfma_f32_16x16x32_bf16 v[74:77], v[180:183], v[214:217], v[74:77]
	v_mfma_f32_16x16x32_bf16 v[70:73], v[146:149], v[222:225], v[70:73]
	v_mfma_f32_16x16x32_bf16 v[66:69], v[180:183], v[222:225], v[66:69]
	v_mfma_f32_16x16x32_bf16 v[98:101], v[194:197], v[210:213], v[82:85]
	v_mfma_f32_16x16x32_bf16 v[78:81], v[150:153], v[218:221], v[78:81]
	v_mfma_f32_16x16x32_bf16 v[74:77], v[194:197], v[218:221], v[74:77]
	v_mfma_f32_16x16x32_bf16 v[70:73], v[150:153], v[226:229], v[70:73]
	v_mfma_f32_16x16x32_bf16 v[66:69], v[194:197], v[226:229], v[66:69]
	s_setprio 0
	s_barrier
	s_add_i32 s72, s72, 2
	s_add_u32 s10, s10, 0x100
	s_addc_u32 s11, s11, 0
	s_add_u32 s31, s31, 0x100
	s_addc_u32 s35, s35, 0
	s_cmp_gt_u32 s72, 13
	s_cbranch_scc0 .LBB0_338
	s_and_b64 vcc, exec, s[28:29]
	s_cbranch_vccz .LBB0_341
	s_barrier

.LBB0_2387:
	ds_read_b128 v[130:133], v213
	ds_read_b128 v[134:137], v213 offset:1024
	ds_read_b128 v[138:141], v213 offset:2048
	ds_read_b128 v[142:145], v213 offset:3072
	ds_read_b128 v[146:149], v214
	ds_read_b128 v[150:153], v214 offset:1024
	ds_read_b128 v[154:157], v214 offset:2048
	ds_read_b128 v[158:161], v214 offset:3072
	s_add_u32 s26, s24, 0xfffc0080
	s_addc_u32 s27, s25, -1
	s_cmp_eq_u32 s55, 12
	s_cselect_b32 s29, s17, s27
	s_cselect_b32 s28, s23, s26
	s_cselect_b32 s27, s15, s54
	s_cselect_b32 s26, s52, s53
	v_lshl_add_u64 v[210:211], s[24:25], 0, v[186:187]
	s_add_i32 m0, s38, 0xc000
	ds_read_b128 v[162:165], v215
	ds_read_b128 v[166:169], v215 offset:1024
	ds_read_b128 v[170:173], v215 offset:2048
	ds_read_b128 v[174:177], v215 offset:3072
	ds_read_b128 v[194:197], v215 offset:4096
	ds_read_b128 v[198:201], v215 offset:5120
	ds_read_b128 v[202:205], v215 offset:6144
	ds_read_b128 v[206:209], v215 offset:7168
	global_load_lds_dwordx4 v[210:211], off
	v_lshl_add_u64 v[210:211], s[24:25], 0, v[188:189]
	s_add_i32 m0, s38, 0xe000
	s_nop 0
	global_load_lds_dwordx4 v[210:211], off
	s_waitcnt vmcnt(8)
	s_waitcnt lgkmcnt(0)
	s_barrier
	s_setprio 1
	v_mfma_f32_16x16x32_bf16 v[126:129], v[130:133], v[162:165], v[126:129]
	v_mfma_f32_16x16x32_bf16 v[122:125], v[138:141], v[162:165], v[122:125]
	v_mfma_f32_16x16x32_bf16 v[110:113], v[130:133], v[170:173], v[110:113]
	v_mfma_f32_16x16x32_bf16 v[106:109], v[138:141], v[170:173], v[106:109]
	v_mfma_f32_16x16x32_bf16 v[94:97], v[130:133], v[194:197], v[94:97]
	v_mfma_f32_16x16x32_bf16 v[90:93], v[138:141], v[194:197], v[90:93]
	v_mfma_f32_16x16x32_bf16 v[78:81], v[130:133], v[202:205], v[78:81]
	v_mfma_f32_16x16x32_bf16 v[74:77], v[138:141], v[202:205], v[74:77]
	v_mfma_f32_16x16x32_bf16 v[126:129], v[134:137], v[166:169], v[126:129]
	v_mfma_f32_16x16x32_bf16 v[122:125], v[142:145], v[166:169], v[122:125]
	v_mfma_f32_16x16x32_bf16 v[110:113], v[134:137], v[174:177], v[110:113]
	v_mfma_f32_16x16x32_bf16 v[106:109], v[142:145], v[174:177], v[106:109]
	v_mfma_f32_16x16x32_bf16 v[94:97], v[134:137], v[198:201], v[94:97]
	v_mfma_f32_16x16x32_bf16 v[90:93], v[142:145], v[198:201], v[90:93]
	v_mfma_f32_16x16x32_bf16 v[78:81], v[134:137], v[206:209], v[78:81]
	v_mfma_f32_16x16x32_bf16 v[74:77], v[142:145], v[206:209], v[74:77]
	v_mfma_f32_16x16x32_bf16 v[118:121], v[146:149], v[162:165], v[118:121]
	v_mfma_f32_16x16x32_bf16 v[114:117], v[154:157], v[162:165], v[114:117]
	v_mfma_f32_16x16x32_bf16 v[102:105], v[146:149], v[170:173], v[102:105]
	v_mfma_f32_16x16x32_bf16 v[98:101], v[154:157], v[170:173], v[98:101]
	v_mfma_f32_16x16x32_bf16 v[86:89], v[146:149], v[194:197], v[86:89]
	v_mfma_f32_16x16x32_bf16 v[82:85], v[154:157], v[194:197], v[82:85]
	v_mfma_f32_16x16x32_bf16 v[70:73], v[146:149], v[202:205], v[70:73]
	v_mfma_f32_16x16x32_bf16 v[66:69], v[154:157], v[202:205], v[66:69]
	v_mfma_f32_16x16x32_bf16 v[118:121], v[150:153], v[166:169], v[118:121]
	v_mfma_f32_16x16x32_bf16 v[114:117], v[158:161], v[166:169], v[114:117]
	v_mfma_f32_16x16x32_bf16 v[102:105], v[150:153], v[174:177], v[102:105]
	v_mfma_f32_16x16x32_bf16 v[98:101], v[158:161], v[174:177], v[98:101]
	v_mfma_f32_16x16x32_bf16 v[86:89], v[150:153], v[198:201], v[86:89]
	v_mfma_f32_16x16x32_bf16 v[82:85], v[158:161], v[198:201], v[82:85]
	v_mfma_f32_16x16x32_bf16 v[70:73], v[150:153], v[206:209], v[70:73]
	v_mfma_f32_16x16x32_bf16 v[66:69], v[158:161], v[206:209], v[66:69]
	s_setprio 0
	s_barrier
	s_add_i32 s56, s47, s37
	v_lshl_add_u64 v[210:211], s[26:27], 0, v[180:181]
	s_mov_b32 m0, s56
	ds_read_b128 v[162:165], v215 offset:16384
	ds_read_b128 v[166:169], v215 offset:17408
	ds_read_b128 v[170:173], v215 offset:18432
	ds_read_b128 v[174:177], v215 offset:19456
	ds_read_b128 v[194:197], v215 offset:20480
	ds_read_b128 v[198:201], v215 offset:21504
	ds_read_b128 v[202:205], v215 offset:22528
	ds_read_b128 v[206:209], v215 offset:23552
	global_load_lds_dwordx4 v[210:211], off
	s_add_i32 m0, s56, 0x2000
	s_add_u32 s56, s26, 0x40000
	v_lshl_add_u64 v[220:221], s[26:27], 0, v[184:185]
	s_addc_u32 s57, s27, 0
	s_add_i32 s58, s48, s37
	global_load_lds_dwordx4 v[220:221], off
	v_lshl_add_u64 v[222:223], s[56:57], 0, v[180:181]
	s_mov_b32 m0, s58
	v_lshl_add_u64 v[224:225], s[28:29], 0, v[182:183]
	global_load_lds_dwordx4 v[222:223], off
	v_lshl_add_u64 v[222:223], s[56:57], 0, v[184:185]
	s_add_i32 m0, s58, 0x2000
	s_nop 0
	global_load_lds_dwordx4 v[222:223], off
	v_lshl_add_u64 v[222:223], s[28:29], 0, v[178:179]
	s_mov_b32 m0, s38
	s_nop 0
	global_load_lds_dwordx4 v[222:223], off
	s_mov_b32 m0, s39
	s_nop 0
	global_load_lds_dwordx4 v[224:225], off
	s_waitcnt vmcnt(8)
	s_waitcnt lgkmcnt(0)
	s_barrier
	s_setprio 1
	v_mfma_f32_16x16x32_bf16 v[62:65], v[130:133], v[162:165], v[62:65]
	v_mfma_f32_16x16x32_bf16 v[58:61], v[138:141], v[162:165], v[58:61]
	v_mfma_f32_16x16x32_bf16 v[46:49], v[130:133], v[170:173], v[46:49]
	v_mfma_f32_16x16x32_bf16 v[42:45], v[138:141], v[170:173], v[42:45]
	v_mfma_f32_16x16x32_bf16 v[30:33], v[130:133], v[194:197], v[30:33]
	v_mfma_f32_16x16x32_bf16 v[26:29], v[138:141], v[194:197], v[26:29]
	v_mfma_f32_16x16x32_bf16 v[14:17], v[130:133], v[202:205], v[14:17]
	v_mfma_f32_16x16x32_bf16 v[10:13], v[138:141], v[202:205], v[10:13]
	v_mfma_f32_16x16x32_bf16 v[62:65], v[134:137], v[166:169], v[62:65]
	v_mfma_f32_16x16x32_bf16 v[58:61], v[142:145], v[166:169], v[58:61]
	v_mfma_f32_16x16x32_bf16 v[46:49], v[134:137], v[174:177], v[46:49]
	v_mfma_f32_16x16x32_bf16 v[42:45], v[142:145], v[174:177], v[42:45]
	v_mfma_f32_16x16x32_bf16 v[30:33], v[134:137], v[198:201], v[30:33]
	v_mfma_f32_16x16x32_bf16 v[26:29], v[142:145], v[198:201], v[26:29]
	v_mfma_f32_16x16x32_bf16 v[14:17], v[134:137], v[206:209], v[14:17]
	v_mfma_f32_16x16x32_bf16 v[10:13], v[142:145], v[206:209], v[10:13]
	v_mfma_f32_16x16x32_bf16 v[54:57], v[146:149], v[162:165], v[54:57]
	v_mfma_f32_16x16x32_bf16 v[50:53], v[154:157], v[162:165], v[50:53]
	v_mfma_f32_16x16x32_bf16 v[38:41], v[146:149], v[170:173], v[38:41]
	v_mfma_f32_16x16x32_bf16 v[34:37], v[154:157], v[170:173], v[34:37]
	v_mfma_f32_16x16x32_bf16 v[22:25], v[146:149], v[194:197], v[22:25]
	v_mfma_f32_16x16x32_bf16 v[18:21], v[154:157], v[194:197], v[18:21]
	v_mfma_f32_16x16x32_bf16 v[6:9], v[146:149], v[202:205], v[6:9]
	v_mfma_f32_16x16x32_bf16 v[2:5], v[154:157], v[202:205], v[2:5]
	v_mfma_f32_16x16x32_bf16 v[54:57], v[150:153], v[166:169], v[54:57]
	v_mfma_f32_16x16x32_bf16 v[50:53], v[158:161], v[166:169], v[50:53]
	v_mfma_f32_16x16x32_bf16 v[38:41], v[150:153], v[174:177], v[38:41]
	v_mfma_f32_16x16x32_bf16 v[34:37], v[158:161], v[174:177], v[34:37]
	v_mfma_f32_16x16x32_bf16 v[22:25], v[150:153], v[198:201], v[22:25]
	v_mfma_f32_16x16x32_bf16 v[18:21], v[158:161], v[198:201], v[18:21]
	v_mfma_f32_16x16x32_bf16 v[6:9], v[150:153], v[206:209], v[6:9]
	v_mfma_f32_16x16x32_bf16 v[2:5], v[158:161], v[206:209], v[2:5]
	s_setprio 0
	s_barrier
	ds_read_b128 v[130:133], v217
	ds_read_b128 v[134:137], v217 offset:1024
	ds_read_b128 v[138:141], v217 offset:2048
	ds_read_b128 v[142:145], v217 offset:3072
	ds_read_b128 v[146:149], v218
	ds_read_b128 v[150:153], v218 offset:1024
	ds_read_b128 v[154:157], v218 offset:2048
	ds_read_b128 v[158:161], v218 offset:3072
	s_add_u32 s28, s28, 0x40000
	s_addc_u32 s29, s29, 0
	s_mov_b32 m0, s40
	v_lshl_add_u64 v[226:227], s[28:29], 0, v[178:179]
	ds_read_b128 v[162:165], v215 offset:32768
	ds_read_b128 v[166:169], v215 offset:33792
	ds_read_b128 v[170:173], v215 offset:34816
	ds_read_b128 v[174:177], v215 offset:35840
	ds_read_b128 v[194:197], v215 offset:36864
	ds_read_b128 v[198:201], v215 offset:37888
	ds_read_b128 v[202:205], v215 offset:38912
	ds_read_b128 v[206:209], v215 offset:39936
	global_load_lds_dwordx4 v[226:227], off
	v_lshl_add_u64 v[226:227], s[28:29], 0, v[182:183]
	s_mov_b32 m0, s41
	s_nop 0
	global_load_lds_dwordx4 v[226:227], off
	s_waitcnt vmcnt(8)
	s_waitcnt lgkmcnt(0)
	s_barrier
	s_setprio 1
	v_mfma_f32_16x16x32_bf16 v[126:129], v[130:133], v[162:165], v[126:129]
	v_mfma_f32_16x16x32_bf16 v[122:125], v[138:141], v[162:165], v[122:125]
	v_mfma_f32_16x16x32_bf16 v[110:113], v[130:133], v[170:173], v[110:113]
	v_mfma_f32_16x16x32_bf16 v[106:109], v[138:141], v[170:173], v[106:109]
	v_mfma_f32_16x16x32_bf16 v[94:97], v[130:133], v[194:197], v[94:97]
	v_mfma_f32_16x16x32_bf16 v[90:93], v[138:141], v[194:197], v[90:93]
	v_mfma_f32_16x16x32_bf16 v[78:81], v[130:133], v[202:205], v[78:81]
	v_mfma_f32_16x16x32_bf16 v[74:77], v[138:141], v[202:205], v[74:77]
	v_mfma_f32_16x16x32_bf16 v[126:129], v[134:137], v[166:169], v[126:129]
	v_mfma_f32_16x16x32_bf16 v[122:125], v[142:145], v[166:169], v[122:125]
	v_mfma_f32_16x16x32_bf16 v[110:113], v[134:137], v[174:177], v[110:113]
	v_mfma_f32_16x16x32_bf16 v[106:109], v[142:145], v[174:177], v[106:109]
	v_mfma_f32_16x16x32_bf16 v[94:97], v[134:137], v[198:201], v[94:97]
	v_mfma_f32_16x16x32_bf16 v[90:93], v[142:145], v[198:201], v[90:93]
	v_mfma_f32_16x16x32_bf16 v[78:81], v[134:137], v[206:209], v[78:81]
	v_mfma_f32_16x16x32_bf16 v[74:77], v[142:145], v[206:209], v[74:77]
	v_mfma_f32_16x16x32_bf16 v[118:121], v[146:149], v[162:165], v[118:121]
	v_mfma_f32_16x16x32_bf16 v[114:117], v[154:157], v[162:165], v[114:117]
	v_mfma_f32_16x16x32_bf16 v[102:105], v[146:149], v[170:173], v[102:105]
	v_mfma_f32_16x16x32_bf16 v[98:101], v[154:157], v[170:173], v[98:101]
	v_mfma_f32_16x16x32_bf16 v[86:89], v[146:149], v[194:197], v[86:89]
	v_mfma_f32_16x16x32_bf16 v[82:85], v[154:157], v[194:197], v[82:85]
	v_mfma_f32_16x16x32_bf16 v[70:73], v[146:149], v[202:205], v[70:73]
	v_mfma_f32_16x16x32_bf16 v[66:69], v[154:157], v[202:205], v[66:69]
	v_mfma_f32_16x16x32_bf16 v[118:121], v[150:153], v[166:169], v[118:121]
	v_mfma_f32_16x16x32_bf16 v[114:117], v[158:161], v[166:169], v[114:117]
	v_mfma_f32_16x16x32_bf16 v[102:105], v[150:153], v[174:177], v[102:105]
	v_mfma_f32_16x16x32_bf16 v[98:101], v[158:161], v[174:177], v[98:101]
	v_mfma_f32_16x16x32_bf16 v[86:89], v[150:153], v[198:201], v[86:89]
	v_mfma_f32_16x16x32_bf16 v[82:85], v[158:161], v[198:201], v[82:85]
	v_mfma_f32_16x16x32_bf16 v[70:73], v[150:153], v[206:209], v[70:73]
	v_mfma_f32_16x16x32_bf16 v[66:69], v[158:161], v[206:209], v[66:69]
	s_setprio 0
	s_barrier
	s_add_i32 s28, s49, s37
	v_lshl_add_u64 v[210:211], v[210:211], 0, s[10:11]
	s_mov_b32 m0, s28
	ds_read_b128 v[162:165], v215 offset:49152
	ds_read_b128 v[166:169], v215 offset:50176
	ds_read_b128 v[170:173], v215 offset:51200
	ds_read_b128 v[174:177], v215 offset:52224
	ds_read_b128 v[194:197], v215 offset:53248
	ds_read_b128 v[198:201], v215 offset:54272
	ds_read_b128 v[202:205], v215 offset:55296
	ds_read_b128 v[206:209], v215 offset:56320
	global_load_lds_dwordx4 v[210:211], off
	s_add_i32 m0, s28, 0x2000
	s_add_u32 s26, s26, 0x40080
	v_lshl_add_u64 v[210:211], v[220:221], 0, s[10:11]
	s_addc_u32 s27, s27, 0
	s_add_i32 s28, s50, s37
	global_load_lds_dwordx4 v[210:211], off
	v_lshl_add_u64 v[210:211], s[26:27], 0, v[180:181]
	s_mov_b32 m0, s28
	s_nop 0
	global_load_lds_dwordx4 v[210:211], off
	v_lshl_add_u64 v[210:211], s[26:27], 0, v[184:185]
	s_add_i32 m0, s28, 0x2000
	s_nop 0
	global_load_lds_dwordx4 v[210:211], off
	v_lshl_add_u64 v[210:211], v[222:223], 0, s[10:11]
	s_mov_b32 m0, s43
	s_nop 0
	global_load_lds_dwordx4 v[210:211], off
	v_lshl_add_u64 v[210:211], v[224:225], 0, s[10:11]
	s_mov_b32 m0, s44
	s_nop 0
	global_load_lds_dwordx4 v[210:211], off
	s_waitcnt vmcnt(8)
	s_waitcnt lgkmcnt(0)
	s_barrier
	s_setprio 1
	v_mfma_f32_16x16x32_bf16 v[62:65], v[130:133], v[162:165], v[62:65]
	v_mfma_f32_16x16x32_bf16 v[58:61], v[138:141], v[162:165], v[58:61]
	v_mfma_f32_16x16x32_bf16 v[46:49], v[130:133], v[170:173], v[46:49]
	v_mfma_f32_16x16x32_bf16 v[42:45], v[138:141], v[170:173], v[42:45]
	v_mfma_f32_16x16x32_bf16 v[30:33], v[130:133], v[194:197], v[30:33]
	v_mfma_f32_16x16x32_bf16 v[26:29], v[138:141], v[194:197], v[26:29]
	v_mfma_f32_16x16x32_bf16 v[14:17], v[130:133], v[202:205], v[14:17]
	v_mfma_f32_16x16x32_bf16 v[10:13], v[138:141], v[202:205], v[10:13]
	v_mfma_f32_16x16x32_bf16 v[62:65], v[134:137], v[166:169], v[62:65]
	v_mfma_f32_16x16x32_bf16 v[58:61], v[142:145], v[166:169], v[58:61]
	v_mfma_f32_16x16x32_bf16 v[46:49], v[134:137], v[174:177], v[46:49]
	v_mfma_f32_16x16x32_bf16 v[42:45], v[142:145], v[174:177], v[42:45]
	v_mfma_f32_16x16x32_bf16 v[30:33], v[134:137], v[198:201], v[30:33]
	v_mfma_f32_16x16x32_bf16 v[26:29], v[142:145], v[198:201], v[26:29]
	v_mfma_f32_16x16x32_bf16 v[14:17], v[134:137], v[206:209], v[14:17]
	v_mfma_f32_16x16x32_bf16 v[10:13], v[142:145], v[206:209], v[10:13]
	v_mfma_f32_16x16x32_bf16 v[54:57], v[146:149], v[162:165], v[54:57]
	v_mfma_f32_16x16x32_bf16 v[50:53], v[154:157], v[162:165], v[50:53]
	v_mfma_f32_16x16x32_bf16 v[38:41], v[146:149], v[170:173], v[38:41]
	v_mfma_f32_16x16x32_bf16 v[34:37], v[154:157], v[170:173], v[34:37]
	v_mfma_f32_16x16x32_bf16 v[22:25], v[146:149], v[194:197], v[22:25]
	v_mfma_f32_16x16x32_bf16 v[18:21], v[154:157], v[194:197], v[18:21]
	v_mfma_f32_16x16x32_bf16 v[6:9], v[146:149], v[202:205], v[6:9]
	v_mfma_f32_16x16x32_bf16 v[2:5], v[154:157], v[202:205], v[2:5]
	v_mfma_f32_16x16x32_bf16 v[54:57], v[150:153], v[166:169], v[54:57]
	v_mfma_f32_16x16x32_bf16 v[50:53], v[158:161], v[166:169], v[50:53]
	v_mfma_f32_16x16x32_bf16 v[38:41], v[150:153], v[174:177], v[38:41]
	v_mfma_f32_16x16x32_bf16 v[34:37], v[158:161], v[174:177], v[34:37]
	v_mfma_f32_16x16x32_bf16 v[22:25], v[150:153], v[198:201], v[22:25]
	v_mfma_f32_16x16x32_bf16 v[18:21], v[158:161], v[198:201], v[18:21]
	v_mfma_f32_16x16x32_bf16 v[6:9], v[150:153], v[206:209], v[6:9]
	v_mfma_f32_16x16x32_bf16 v[2:5], v[158:161], v[206:209], v[2:5]
	s_setprio 0
	s_barrier
	s_add_i32 s55, s55, 2
	s_add_u32 s24, s24, 0x100
	s_addc_u32 s25, s25, 0
	s_add_u32 s53, s53, 0x100
	s_addc_u32 s54, s54, 0
	s_cmp_gt_u32 s55, 13
	s_cbranch_scc0 .LBB0_2387
	v_lshl_add_u32 v198, s22, 8, v1
	v_lshl_or_b32 v194, s12, 8, v212
	v_ashrrev_i32_e32 v195, 31, v194
	v_ashrrev_i32_e32 v199, 31, v198
	v_lshl_add_u64 v[196:197], v[194:195], 2, s[62:63]
	v_lshlrev_b64 v[130:131], 12, v[198:199]
	v_lshl_add_u64 v[236:237], v[196:197], 0, v[130:131]
	global_load_dwordx4 v[220:223], v[236:237], off nt
	global_load_dwordx4 v[224:227], v[236:237], off offset:16 nt
	global_load_dwordx4 v[228:231], v[236:237], off offset:512 nt
	global_load_dwordx4 v[232:235], v[236:237], off offset:528 nt
	v_or_b32_e32 v208, 16, v198
	v_or_b32_e32 v204, 32, v198
	v_or_b32_e32 v200, 48, v198
	v_ashrrev_i32_e32 v209, 31, v208
	v_ashrrev_i32_e32 v205, 31, v204
	v_ashrrev_i32_e32 v201, 31, v200
	v_lshlrev_b64 v[130:131], 12, v[208:209]
	v_lshlrev_b64 v[132:133], 12, v[204:205]
	v_lshlrev_b64 v[134:135], 12, v[200:201]
	v_lshl_add_u64 v[210:211], v[196:197], 0, v[130:131]
	v_lshl_add_u64 v[206:207], v[196:197], 0, v[132:133]
	v_lshl_add_u64 v[202:203], v[196:197], 0, v[134:135]
	global_load_dwordx4 v[170:173], v[210:211], off offset:16 nt
	global_load_dwordx4 v[174:177], v[210:211], off nt
	global_load_dwordx4 v[162:165], v[210:211], off offset:528 nt
	global_load_dwordx4 v[166:169], v[210:211], off offset:512 nt
	global_load_dwordx4 v[154:157], v[206:207], off offset:16 nt
	global_load_dwordx4 v[158:161], v[206:207], off nt
	global_load_dwordx4 v[146:149], v[206:207], off offset:528 nt
	global_load_dwordx4 v[150:153], v[206:207], off offset:512 nt
	global_load_dwordx4 v[138:141], v[202:203], off offset:16 nt
	global_load_dwordx4 v[142:145], v[202:203], off nt
	global_load_dwordx4 v[130:133], v[202:203], off offset:528 nt
	global_load_dwordx4 v[134:137], v[202:203], off offset:512 nt
	v_and_b32_e32 v238, 64, v216
	v_xor_b32_e32 v219, 16, v216
	v_add_u32_e32 v241, 64, v238
	v_cmp_lt_i32_e32 vcc, v219, v241
	v_lshlrev_b64 v[238:239], 10, v[198:199]
	v_xor_b32_e32 v240, 32, v216
	v_cndmask_b32_e32 v219, v216, v219, vcc
	v_lshlrev_b32_e32 v219, 2, v219
	v_lshl_add_u64 v[238:239], v[238:239], 0, v[194:195]
	v_cmp_lt_i32_e32 vcc, v240, v241
	v_lshlrev_b64 v[238:239], 1, v[238:239]
	s_lshl_b32 s22, s12, 2
	v_cndmask_b32_e32 v242, v216, v240, vcc
	v_lshl_add_u64 v[240:241], s[2:3], 0, v[238:239]
	v_or_b32_e32 v238, 0x100, v238
	s_ashr_i32 s23, s22, 31
	s_waitcnt vmcnt(0)
	v_pk_add_f32 v[128:129], v[128:129], v[222:223]
	v_pk_add_f32 v[126:127], v[126:127], v[220:221]
	v_pk_add_f32 v[120:121], v[120:121], v[230:231]
	v_pk_add_f32 v[118:119], v[118:119], v[228:229]
	v_pk_add_f32 v[124:125], v[124:125], v[226:227]
	v_pk_add_f32 v[122:123], v[122:123], v[224:225]
	v_pk_add_f32 v[114:115], v[114:115], v[232:233]
	global_store_dwordx4 v[236:237], v[126:129], off nt
	global_store_dwordx4 v[236:237], v[122:125], off offset:16 nt
	v_cvt_pk_bf16_f32 v220, v126, v127
	v_cvt_pk_bf16_f32 v221, v128, v129
	v_mul_f32_e32 v224, v119, v119
	v_mul_f32_e32 v127, v127, v127
	v_mul_f32_e32 v129, v129, v129
	v_mul_f32_e32 v225, v121, v121
	v_pk_add_f32 v[116:117], v[116:117], v[234:235]
	v_cvt_pk_bf16_f32 v222, v122, v123
	v_cvt_pk_bf16_f32 v223, v124, v125
	v_mul_f32_e32 v123, v123, v123
	v_mul_f32_e32 v125, v125, v125
	v_mul_f32_e32 v226, v115, v115
	v_fmac_f32_e32 v127, v126, v126
	v_fmac_f32_e32 v129, v128, v128
	v_fmac_f32_e32 v224, v118, v118
	v_fmac_f32_e32 v225, v120, v120
	v_mul_f32_e32 v227, v117, v117
	v_fmac_f32_e32 v123, v122, v122
	v_fmac_f32_e32 v125, v124, v124
	v_fmac_f32_e32 v226, v114, v114
	v_add_f32_e32 v122, v127, v129
	v_add_f32_e32 v124, v224, v225
	v_fmac_f32_e32 v227, v116, v116
	v_add_f32_e32 v122, v122, v123
	v_add_f32_e32 v123, v124, v226
	v_add_f32_e32 v122, v125, v122
	v_add_f32_e32 v123, v227, v123
	v_add_f32_e32 v122, v122, v123
	ds_bpermute_b32 v123, v219, v122
	global_store_dwordx4 v[240:241], v[220:223], off
	global_store_dwordx4 v[236:237], v[118:121], off offset:512 nt
	global_store_dwordx4 v[236:237], v[114:117], off offset:528 nt
	v_lshlrev_b32_e32 v128, 2, v242
	v_cvt_pk_bf16_f32 v118, v118, v119
	v_cvt_pk_bf16_f32 v119, v120, v121
	v_cvt_pk_bf16_f32 v120, v114, v115
	v_cvt_pk_bf16_f32 v121, v116, v117
	s_waitcnt lgkmcnt(0)
	v_add_f32_e32 v114, v122, v123
	ds_bpermute_b32 v115, v128, v114
	v_lshl_add_u64 v[116:117], s[2:3], 0, v[238:239]
	global_store_dwordx4 v[116:117], v[118:121], off
	s_and_saveexec_b64 s[24:25], s[4:5]
	s_cbranch_execz .LBB0_2390
	s_waitcnt lgkmcnt(0)
	v_add_f32_e32 v116, v114, v115
	v_lshlrev_b64 v[114:115], 6, v[198:199]
	v_lshl_add_u64 v[114:115], s[8:9], 0, v[114:115]
	v_lshl_add_u64 v[114:115], s[22:23], 2, v[114:115]
	s_lshl_b32 s12, s42, 2
	v_lshl_add_u64 v[114:115], v[114:115], 0, s[12:13]
	global_store_dword v[114:115], v116, off

.LBB0_2471:
	ds_read_b128 v[130:133], v213
	ds_read_b128 v[134:137], v213 offset:1024
	ds_read_b128 v[138:141], v213 offset:2048
	ds_read_b128 v[142:145], v213 offset:3072
	ds_read_b128 v[146:149], v214
	ds_read_b128 v[150:153], v214 offset:1024
	ds_read_b128 v[154:157], v214 offset:2048
	ds_read_b128 v[158:161], v214 offset:3072
	s_add_u32 s20, s18, 0xfff50080
	s_addc_u32 s21, s19, -1
	s_cmp_eq_u32 s51, 40
	s_cselect_b32 s23, s9, s21
	s_cselect_b32 s22, s8, s20
	s_cselect_b32 s21, s11, s50
	s_cselect_b32 s20, s10, s49
	v_lshl_add_u64 v[210:211], s[18:19], 0, v[186:187]
	s_add_i32 m0, s31, 0xc000
	ds_read_b128 v[162:165], v215
	ds_read_b128 v[166:169], v215 offset:1024
	ds_read_b128 v[170:173], v215 offset:2048
	ds_read_b128 v[174:177], v215 offset:3072
	ds_read_b128 v[194:197], v215 offset:4096
	ds_read_b128 v[198:201], v215 offset:5120
	ds_read_b128 v[202:205], v215 offset:6144
	ds_read_b128 v[206:209], v215 offset:7168
	global_load_lds_dwordx4 v[210:211], off
	v_lshl_add_u64 v[210:211], s[18:19], 0, v[188:189]
	s_add_i32 m0, s31, 0xe000
	s_nop 0
	global_load_lds_dwordx4 v[210:211], off
	s_waitcnt vmcnt(8)
	s_waitcnt lgkmcnt(0)
	s_barrier
	s_setprio 1
	v_mfma_f32_16x16x32_bf16 v[126:129], v[130:133], v[162:165], v[126:129]
	v_mfma_f32_16x16x32_bf16 v[122:125], v[138:141], v[162:165], v[122:125]
	v_mfma_f32_16x16x32_bf16 v[110:113], v[130:133], v[170:173], v[110:113]
	v_mfma_f32_16x16x32_bf16 v[106:109], v[138:141], v[170:173], v[106:109]
	v_mfma_f32_16x16x32_bf16 v[94:97], v[130:133], v[194:197], v[94:97]
	v_mfma_f32_16x16x32_bf16 v[90:93], v[138:141], v[194:197], v[90:93]
	v_mfma_f32_16x16x32_bf16 v[78:81], v[130:133], v[202:205], v[78:81]
	v_mfma_f32_16x16x32_bf16 v[74:77], v[138:141], v[202:205], v[74:77]
	v_mfma_f32_16x16x32_bf16 v[126:129], v[134:137], v[166:169], v[126:129]
	v_mfma_f32_16x16x32_bf16 v[122:125], v[142:145], v[166:169], v[122:125]
	v_mfma_f32_16x16x32_bf16 v[110:113], v[134:137], v[174:177], v[110:113]
	v_mfma_f32_16x16x32_bf16 v[106:109], v[142:145], v[174:177], v[106:109]
	v_mfma_f32_16x16x32_bf16 v[94:97], v[134:137], v[198:201], v[94:97]
	v_mfma_f32_16x16x32_bf16 v[90:93], v[142:145], v[198:201], v[90:93]
	v_mfma_f32_16x16x32_bf16 v[78:81], v[134:137], v[206:209], v[78:81]
	v_mfma_f32_16x16x32_bf16 v[74:77], v[142:145], v[206:209], v[74:77]
	v_mfma_f32_16x16x32_bf16 v[118:121], v[146:149], v[162:165], v[118:121]
	v_mfma_f32_16x16x32_bf16 v[114:117], v[154:157], v[162:165], v[114:117]
	v_mfma_f32_16x16x32_bf16 v[102:105], v[146:149], v[170:173], v[102:105]
	v_mfma_f32_16x16x32_bf16 v[98:101], v[154:157], v[170:173], v[98:101]
	v_mfma_f32_16x16x32_bf16 v[86:89], v[146:149], v[194:197], v[86:89]
	v_mfma_f32_16x16x32_bf16 v[82:85], v[154:157], v[194:197], v[82:85]
	v_mfma_f32_16x16x32_bf16 v[70:73], v[146:149], v[202:205], v[70:73]
	v_mfma_f32_16x16x32_bf16 v[66:69], v[154:157], v[202:205], v[66:69]
	v_mfma_f32_16x16x32_bf16 v[118:121], v[150:153], v[166:169], v[118:121]
	v_mfma_f32_16x16x32_bf16 v[114:117], v[158:161], v[166:169], v[114:117]
	v_mfma_f32_16x16x32_bf16 v[102:105], v[150:153], v[174:177], v[102:105]
	v_mfma_f32_16x16x32_bf16 v[98:101], v[158:161], v[174:177], v[98:101]
	v_mfma_f32_16x16x32_bf16 v[86:89], v[150:153], v[198:201], v[86:89]
	v_mfma_f32_16x16x32_bf16 v[82:85], v[158:161], v[198:201], v[82:85]
	v_mfma_f32_16x16x32_bf16 v[70:73], v[150:153], v[206:209], v[70:73]
	v_mfma_f32_16x16x32_bf16 v[66:69], v[158:161], v[206:209], v[66:69]
	s_setprio 0
	s_barrier
	s_add_i32 s52, s41, s30
	v_lshl_add_u64 v[210:211], s[20:21], 0, v[180:181]
	s_mov_b32 m0, s52
	ds_read_b128 v[162:165], v215 offset:16384
	ds_read_b128 v[166:169], v215 offset:17408
	ds_read_b128 v[170:173], v215 offset:18432
	ds_read_b128 v[174:177], v215 offset:19456
	ds_read_b128 v[194:197], v215 offset:20480
	ds_read_b128 v[198:201], v215 offset:21504
	ds_read_b128 v[202:205], v215 offset:22528
	ds_read_b128 v[206:209], v215 offset:23552
	global_load_lds_dwordx4 v[210:211], off
	s_add_i32 m0, s52, 0x2000
	s_add_u32 s52, s20, 0xb0000
	v_lshl_add_u64 v[220:221], s[20:21], 0, v[184:185]
	s_addc_u32 s53, s21, 0
	s_add_i32 s54, s42, s30
	global_load_lds_dwordx4 v[220:221], off
	v_lshl_add_u64 v[222:223], s[52:53], 0, v[180:181]
	s_mov_b32 m0, s54
	v_lshl_add_u64 v[224:225], s[22:23], 0, v[182:183]
	global_load_lds_dwordx4 v[222:223], off
	v_lshl_add_u64 v[222:223], s[52:53], 0, v[184:185]
	s_add_i32 m0, s54, 0x2000
	s_nop 0
	global_load_lds_dwordx4 v[222:223], off
	v_lshl_add_u64 v[222:223], s[22:23], 0, v[178:179]
	s_mov_b32 m0, s31
	s_nop 0
	global_load_lds_dwordx4 v[222:223], off
	s_mov_b32 m0, s33
	s_nop 0
	global_load_lds_dwordx4 v[224:225], off
	s_waitcnt vmcnt(8)
	s_waitcnt lgkmcnt(0)
	s_barrier
	s_setprio 1
	v_mfma_f32_16x16x32_bf16 v[62:65], v[130:133], v[162:165], v[62:65]
	v_mfma_f32_16x16x32_bf16 v[58:61], v[138:141], v[162:165], v[58:61]
	v_mfma_f32_16x16x32_bf16 v[46:49], v[130:133], v[170:173], v[46:49]
	v_mfma_f32_16x16x32_bf16 v[42:45], v[138:141], v[170:173], v[42:45]
	v_mfma_f32_16x16x32_bf16 v[30:33], v[130:133], v[194:197], v[30:33]
	v_mfma_f32_16x16x32_bf16 v[26:29], v[138:141], v[194:197], v[26:29]
	v_mfma_f32_16x16x32_bf16 v[14:17], v[130:133], v[202:205], v[14:17]
	v_mfma_f32_16x16x32_bf16 v[10:13], v[138:141], v[202:205], v[10:13]
	v_mfma_f32_16x16x32_bf16 v[62:65], v[134:137], v[166:169], v[62:65]
	v_mfma_f32_16x16x32_bf16 v[58:61], v[142:145], v[166:169], v[58:61]
	v_mfma_f32_16x16x32_bf16 v[46:49], v[134:137], v[174:177], v[46:49]
	v_mfma_f32_16x16x32_bf16 v[42:45], v[142:145], v[174:177], v[42:45]
	v_mfma_f32_16x16x32_bf16 v[30:33], v[134:137], v[198:201], v[30:33]
	v_mfma_f32_16x16x32_bf16 v[26:29], v[142:145], v[198:201], v[26:29]
	v_mfma_f32_16x16x32_bf16 v[14:17], v[134:137], v[206:209], v[14:17]
	v_mfma_f32_16x16x32_bf16 v[10:13], v[142:145], v[206:209], v[10:13]
	v_mfma_f32_16x16x32_bf16 v[54:57], v[146:149], v[162:165], v[54:57]
	v_mfma_f32_16x16x32_bf16 v[50:53], v[154:157], v[162:165], v[50:53]
	v_mfma_f32_16x16x32_bf16 v[38:41], v[146:149], v[170:173], v[38:41]
	v_mfma_f32_16x16x32_bf16 v[34:37], v[154:157], v[170:173], v[34:37]
	v_mfma_f32_16x16x32_bf16 v[22:25], v[146:149], v[194:197], v[22:25]
	v_mfma_f32_16x16x32_bf16 v[18:21], v[154:157], v[194:197], v[18:21]
	v_mfma_f32_16x16x32_bf16 v[6:9], v[146:149], v[202:205], v[6:9]
	v_mfma_f32_16x16x32_bf16 v[2:5], v[154:157], v[202:205], v[2:5]
	v_mfma_f32_16x16x32_bf16 v[54:57], v[150:153], v[166:169], v[54:57]
	v_mfma_f32_16x16x32_bf16 v[50:53], v[158:161], v[166:169], v[50:53]
	v_mfma_f32_16x16x32_bf16 v[38:41], v[150:153], v[174:177], v[38:41]
	v_mfma_f32_16x16x32_bf16 v[34:37], v[158:161], v[174:177], v[34:37]
	v_mfma_f32_16x16x32_bf16 v[22:25], v[150:153], v[198:201], v[22:25]
	v_mfma_f32_16x16x32_bf16 v[18:21], v[158:161], v[198:201], v[18:21]
	v_mfma_f32_16x16x32_bf16 v[6:9], v[150:153], v[206:209], v[6:9]
	v_mfma_f32_16x16x32_bf16 v[2:5], v[158:161], v[206:209], v[2:5]
	s_setprio 0
	s_barrier
	ds_read_b128 v[130:133], v217
	ds_read_b128 v[134:137], v217 offset:1024
	ds_read_b128 v[138:141], v217 offset:2048
	ds_read_b128 v[142:145], v217 offset:3072
	ds_read_b128 v[146:149], v218
	ds_read_b128 v[150:153], v218 offset:1024
	ds_read_b128 v[154:157], v218 offset:2048
	ds_read_b128 v[158:161], v218 offset:3072
	s_add_u32 s22, s22, 0xb0000
	s_addc_u32 s23, s23, 0
	s_mov_b32 m0, s34
	v_lshl_add_u64 v[226:227], s[22:23], 0, v[178:179]
	ds_read_b128 v[162:165], v215 offset:32768
	ds_read_b128 v[166:169], v215 offset:33792
	ds_read_b128 v[170:173], v215 offset:34816
	ds_read_b128 v[174:177], v215 offset:35840
	ds_read_b128 v[194:197], v215 offset:36864
	ds_read_b128 v[198:201], v215 offset:37888
	ds_read_b128 v[202:205], v215 offset:38912
	ds_read_b128 v[206:209], v215 offset:39936
	global_load_lds_dwordx4 v[226:227], off
	v_lshl_add_u64 v[226:227], s[22:23], 0, v[182:183]
	s_mov_b32 m0, s35
	s_nop 0
	global_load_lds_dwordx4 v[226:227], off
	s_waitcnt vmcnt(8)
	s_waitcnt lgkmcnt(0)
	s_barrier
	s_setprio 1
	v_mfma_f32_16x16x32_bf16 v[126:129], v[130:133], v[162:165], v[126:129]
	v_mfma_f32_16x16x32_bf16 v[122:125], v[138:141], v[162:165], v[122:125]
	v_mfma_f32_16x16x32_bf16 v[110:113], v[130:133], v[170:173], v[110:113]
	v_mfma_f32_16x16x32_bf16 v[106:109], v[138:141], v[170:173], v[106:109]
	v_mfma_f32_16x16x32_bf16 v[94:97], v[130:133], v[194:197], v[94:97]
	v_mfma_f32_16x16x32_bf16 v[90:93], v[138:141], v[194:197], v[90:93]
	v_mfma_f32_16x16x32_bf16 v[78:81], v[130:133], v[202:205], v[78:81]
	v_mfma_f32_16x16x32_bf16 v[74:77], v[138:141], v[202:205], v[74:77]
	v_mfma_f32_16x16x32_bf16 v[126:129], v[134:137], v[166:169], v[126:129]
	v_mfma_f32_16x16x32_bf16 v[122:125], v[142:145], v[166:169], v[122:125]
	v_mfma_f32_16x16x32_bf16 v[110:113], v[134:137], v[174:177], v[110:113]
	v_mfma_f32_16x16x32_bf16 v[106:109], v[142:145], v[174:177], v[106:109]
	v_mfma_f32_16x16x32_bf16 v[94:97], v[134:137], v[198:201], v[94:97]
	v_mfma_f32_16x16x32_bf16 v[90:93], v[142:145], v[198:201], v[90:93]
	v_mfma_f32_16x16x32_bf16 v[78:81], v[134:137], v[206:209], v[78:81]
	v_mfma_f32_16x16x32_bf16 v[74:77], v[142:145], v[206:209], v[74:77]
	v_mfma_f32_16x16x32_bf16 v[118:121], v[146:149], v[162:165], v[118:121]
	v_mfma_f32_16x16x32_bf16 v[114:117], v[154:157], v[162:165], v[114:117]
	v_mfma_f32_16x16x32_bf16 v[102:105], v[146:149], v[170:173], v[102:105]
	v_mfma_f32_16x16x32_bf16 v[98:101], v[154:157], v[170:173], v[98:101]
	v_mfma_f32_16x16x32_bf16 v[86:89], v[146:149], v[194:197], v[86:89]
	v_mfma_f32_16x16x32_bf16 v[82:85], v[154:157], v[194:197], v[82:85]
	v_mfma_f32_16x16x32_bf16 v[70:73], v[146:149], v[202:205], v[70:73]
	v_mfma_f32_16x16x32_bf16 v[66:69], v[154:157], v[202:205], v[66:69]
	v_mfma_f32_16x16x32_bf16 v[118:121], v[150:153], v[166:169], v[118:121]
	v_mfma_f32_16x16x32_bf16 v[114:117], v[158:161], v[166:169], v[114:117]
	v_mfma_f32_16x16x32_bf16 v[102:105], v[150:153], v[174:177], v[102:105]
	v_mfma_f32_16x16x32_bf16 v[98:101], v[158:161], v[174:177], v[98:101]
	v_mfma_f32_16x16x32_bf16 v[86:89], v[150:153], v[198:201], v[86:89]
	v_mfma_f32_16x16x32_bf16 v[82:85], v[158:161], v[198:201], v[82:85]
	v_mfma_f32_16x16x32_bf16 v[70:73], v[150:153], v[206:209], v[70:73]
	v_mfma_f32_16x16x32_bf16 v[66:69], v[158:161], v[206:209], v[66:69]
	s_setprio 0
	s_barrier
	s_add_i32 s22, s43, s30
	v_lshl_add_u64 v[210:211], v[210:211], 0, s[14:15]
	s_mov_b32 m0, s22
	ds_read_b128 v[162:165], v215 offset:49152
	ds_read_b128 v[166:169], v215 offset:50176
	ds_read_b128 v[170:173], v215 offset:51200
	ds_read_b128 v[174:177], v215 offset:52224
	ds_read_b128 v[194:197], v215 offset:53248
	ds_read_b128 v[198:201], v215 offset:54272
	ds_read_b128 v[202:205], v215 offset:55296
	ds_read_b128 v[206:209], v215 offset:56320
	global_load_lds_dwordx4 v[210:211], off
	s_add_i32 m0, s22, 0x2000
	s_add_u32 s20, s20, 0xb0080
	v_lshl_add_u64 v[210:211], v[220:221], 0, s[14:15]
	s_addc_u32 s21, s21, 0
	s_add_i32 s22, s44, s30
	global_load_lds_dwordx4 v[210:211], off
	v_lshl_add_u64 v[210:211], s[20:21], 0, v[180:181]
	s_mov_b32 m0, s22
	s_nop 0
	global_load_lds_dwordx4 v[210:211], off
	v_lshl_add_u64 v[210:211], s[20:21], 0, v[184:185]
	s_add_i32 m0, s22, 0x2000
	s_nop 0
	global_load_lds_dwordx4 v[210:211], off
	v_lshl_add_u64 v[210:211], v[222:223], 0, s[14:15]
	s_mov_b32 m0, s37
	s_nop 0
	global_load_lds_dwordx4 v[210:211], off
	v_lshl_add_u64 v[210:211], v[224:225], 0, s[14:15]
	s_mov_b32 m0, s38
	s_nop 0
	global_load_lds_dwordx4 v[210:211], off
	s_waitcnt vmcnt(8)
	s_waitcnt lgkmcnt(0)
	s_barrier
	s_setprio 1
	v_mfma_f32_16x16x32_bf16 v[62:65], v[130:133], v[162:165], v[62:65]
	v_mfma_f32_16x16x32_bf16 v[58:61], v[138:141], v[162:165], v[58:61]
	v_mfma_f32_16x16x32_bf16 v[46:49], v[130:133], v[170:173], v[46:49]
	v_mfma_f32_16x16x32_bf16 v[42:45], v[138:141], v[170:173], v[42:45]
	v_mfma_f32_16x16x32_bf16 v[30:33], v[130:133], v[194:197], v[30:33]
	v_mfma_f32_16x16x32_bf16 v[26:29], v[138:141], v[194:197], v[26:29]
	v_mfma_f32_16x16x32_bf16 v[14:17], v[130:133], v[202:205], v[14:17]
	v_mfma_f32_16x16x32_bf16 v[10:13], v[138:141], v[202:205], v[10:13]
	v_mfma_f32_16x16x32_bf16 v[62:65], v[134:137], v[166:169], v[62:65]
	v_mfma_f32_16x16x32_bf16 v[58:61], v[142:145], v[166:169], v[58:61]
	v_mfma_f32_16x16x32_bf16 v[46:49], v[134:137], v[174:177], v[46:49]
	v_mfma_f32_16x16x32_bf16 v[42:45], v[142:145], v[174:177], v[42:45]
	v_mfma_f32_16x16x32_bf16 v[30:33], v[134:137], v[198:201], v[30:33]
	v_mfma_f32_16x16x32_bf16 v[26:29], v[142:145], v[198:201], v[26:29]
	v_mfma_f32_16x16x32_bf16 v[14:17], v[134:137], v[206:209], v[14:17]
	v_mfma_f32_16x16x32_bf16 v[10:13], v[142:145], v[206:209], v[10:13]
	v_mfma_f32_16x16x32_bf16 v[54:57], v[146:149], v[162:165], v[54:57]
	v_mfma_f32_16x16x32_bf16 v[50:53], v[154:157], v[162:165], v[50:53]
	v_mfma_f32_16x16x32_bf16 v[38:41], v[146:149], v[170:173], v[38:41]
	v_mfma_f32_16x16x32_bf16 v[34:37], v[154:157], v[170:173], v[34:37]
	v_mfma_f32_16x16x32_bf16 v[22:25], v[146:149], v[194:197], v[22:25]
	v_mfma_f32_16x16x32_bf16 v[18:21], v[154:157], v[194:197], v[18:21]
	v_mfma_f32_16x16x32_bf16 v[6:9], v[146:149], v[202:205], v[6:9]
	v_mfma_f32_16x16x32_bf16 v[2:5], v[154:157], v[202:205], v[2:5]
	v_mfma_f32_16x16x32_bf16 v[54:57], v[150:153], v[166:169], v[54:57]
	v_mfma_f32_16x16x32_bf16 v[50:53], v[158:161], v[166:169], v[50:53]
	v_mfma_f32_16x16x32_bf16 v[38:41], v[150:153], v[174:177], v[38:41]
	v_mfma_f32_16x16x32_bf16 v[34:37], v[158:161], v[174:177], v[34:37]
	v_mfma_f32_16x16x32_bf16 v[22:25], v[150:153], v[198:201], v[22:25]
	v_mfma_f32_16x16x32_bf16 v[18:21], v[158:161], v[198:201], v[18:21]
	v_mfma_f32_16x16x32_bf16 v[6:9], v[150:153], v[206:209], v[6:9]
	v_mfma_f32_16x16x32_bf16 v[2:5], v[158:161], v[206:209], v[2:5]
	s_setprio 0
	s_barrier
	s_add_i32 s51, s51, 2
	s_add_u32 s18, s18, 0x100
	s_addc_u32 s19, s19, 0
	s_add_u32 s49, s49, 0x100
	s_addc_u32 s50, s50, 0
	s_cmp_gt_u32 s51, 41
	s_cbranch_scc0 .LBB0_2471
	v_lshl_add_u32 v198, s48, 8, v1
	v_lshl_or_b32 v194, s16, 8, v212
	v_ashrrev_i32_e32 v195, 31, v194
	v_ashrrev_i32_e32 v199, 31, v198
	v_lshl_add_u64 v[196:197], v[194:195], 2, s[62:63]
	v_lshlrev_b64 v[130:131], 12, v[198:199]
	v_lshl_add_u64 v[236:237], v[196:197], 0, v[130:131]
	global_load_dwordx4 v[220:223], v[236:237], off nt
	global_load_dwordx4 v[224:227], v[236:237], off offset:16 nt
	global_load_dwordx4 v[228:231], v[236:237], off offset:512 nt
	global_load_dwordx4 v[232:235], v[236:237], off offset:528 nt
	v_or_b32_e32 v208, 16, v198
	v_or_b32_e32 v204, 32, v198
	v_or_b32_e32 v200, 48, v198
	v_ashrrev_i32_e32 v209, 31, v208
	v_ashrrev_i32_e32 v205, 31, v204
	v_ashrrev_i32_e32 v201, 31, v200
	v_lshlrev_b64 v[130:131], 12, v[208:209]
	v_lshlrev_b64 v[132:133], 12, v[204:205]
	v_lshlrev_b64 v[134:135], 12, v[200:201]
	v_lshl_add_u64 v[210:211], v[196:197], 0, v[130:131]
	v_lshl_add_u64 v[206:207], v[196:197], 0, v[132:133]
	v_lshl_add_u64 v[202:203], v[196:197], 0, v[134:135]
	global_load_dwordx4 v[170:173], v[210:211], off offset:16 nt
	global_load_dwordx4 v[174:177], v[210:211], off nt
	global_load_dwordx4 v[162:165], v[210:211], off offset:528 nt
	global_load_dwordx4 v[166:169], v[210:211], off offset:512 nt
	global_load_dwordx4 v[154:157], v[206:207], off offset:16 nt
	global_load_dwordx4 v[158:161], v[206:207], off nt
	global_load_dwordx4 v[146:149], v[206:207], off offset:528 nt
	global_load_dwordx4 v[150:153], v[206:207], off offset:512 nt
	global_load_dwordx4 v[138:141], v[202:203], off offset:16 nt
	global_load_dwordx4 v[142:145], v[202:203], off nt
	global_load_dwordx4 v[130:133], v[202:203], off offset:528 nt
	global_load_dwordx4 v[134:137], v[202:203], off offset:512 nt
	v_and_b32_e32 v238, 64, v216
	v_xor_b32_e32 v219, 16, v216
	v_add_u32_e32 v241, 64, v238
	v_cmp_lt_i32_e32 vcc, v219, v241
	v_lshlrev_b64 v[238:239], 10, v[198:199]
	v_xor_b32_e32 v240, 32, v216
	v_cndmask_b32_e32 v219, v216, v219, vcc
	v_lshlrev_b32_e32 v219, 2, v219
	v_lshl_add_u64 v[238:239], v[238:239], 0, v[194:195]
	v_cmp_lt_i32_e32 vcc, v240, v241
	v_lshlrev_b64 v[238:239], 1, v[238:239]
	s_lshl_b32 s18, s16, 2
	v_cndmask_b32_e32 v242, v216, v240, vcc
	v_lshl_add_u64 v[240:241], s[2:3], 0, v[238:239]
	v_or_b32_e32 v238, 0x100, v238
	s_ashr_i32 s19, s18, 31
	s_waitcnt vmcnt(0)
	v_pk_fma_f32 v[128:129], v[128:129], 0.5, v[222:223] op_sel_hi:[1,0,1]
	v_pk_fma_f32 v[126:127], v[126:127], 0.5, v[220:221] op_sel_hi:[1,0,1]
	v_pk_fma_f32 v[120:121], v[120:121], 0.5, v[230:231] op_sel_hi:[1,0,1]
	v_pk_fma_f32 v[118:119], v[118:119], 0.5, v[228:229] op_sel_hi:[1,0,1]
	v_pk_fma_f32 v[124:125], v[124:125], 0.5, v[226:227] op_sel_hi:[1,0,1]
	v_pk_fma_f32 v[122:123], v[122:123], 0.5, v[224:225] op_sel_hi:[1,0,1]
	v_pk_fma_f32 v[114:115], v[114:115], 0.5, v[232:233] op_sel_hi:[1,0,1]
	global_store_dwordx4 v[236:237], v[126:129], off nt
	global_store_dwordx4 v[236:237], v[122:125], off offset:16 nt
	v_cvt_pk_bf16_f32 v220, v126, v127
	v_cvt_pk_bf16_f32 v221, v128, v129
	v_mul_f32_e32 v224, v119, v119
	v_mul_f32_e32 v127, v127, v127
	v_mul_f32_e32 v129, v129, v129
	v_mul_f32_e32 v225, v121, v121
	v_pk_fma_f32 v[116:117], v[116:117], 0.5, v[234:235] op_sel_hi:[1,0,1]
	v_cvt_pk_bf16_f32 v222, v122, v123
	v_cvt_pk_bf16_f32 v223, v124, v125
	v_mul_f32_e32 v123, v123, v123
	v_mul_f32_e32 v125, v125, v125
	v_mul_f32_e32 v226, v115, v115
	v_fmac_f32_e32 v127, v126, v126
	v_fmac_f32_e32 v129, v128, v128
	v_fmac_f32_e32 v224, v118, v118
	v_fmac_f32_e32 v225, v120, v120
	v_mul_f32_e32 v227, v117, v117
	v_fmac_f32_e32 v123, v122, v122
	v_fmac_f32_e32 v125, v124, v124
	v_fmac_f32_e32 v226, v114, v114
	v_add_f32_e32 v122, v127, v129
	v_add_f32_e32 v124, v224, v225
	v_fmac_f32_e32 v227, v116, v116
	v_add_f32_e32 v122, v122, v123
	v_add_f32_e32 v123, v124, v226
	v_add_f32_e32 v122, v125, v122
	v_add_f32_e32 v123, v227, v123
	v_add_f32_e32 v122, v122, v123
	ds_bpermute_b32 v123, v219, v122
	global_store_dwordx4 v[240:241], v[220:223], off
	global_store_dwordx4 v[236:237], v[118:121], off offset:512 nt
	global_store_dwordx4 v[236:237], v[114:117], off offset:528 nt
	v_lshlrev_b32_e32 v128, 2, v242
	v_cvt_pk_bf16_f32 v118, v118, v119
	v_cvt_pk_bf16_f32 v119, v120, v121
	v_cvt_pk_bf16_f32 v120, v114, v115
	v_cvt_pk_bf16_f32 v121, v116, v117
	s_waitcnt lgkmcnt(0)
	v_add_f32_e32 v114, v122, v123
	ds_bpermute_b32 v115, v128, v114
	v_lshl_add_u64 v[116:117], s[2:3], 0, v[238:239]
	global_store_dwordx4 v[116:117], v[118:121], off
	s_and_saveexec_b64 s[20:21], s[4:5]
	s_cbranch_execz .LBB0_2474
	s_waitcnt lgkmcnt(0)
	v_add_f32_e32 v116, v114, v115
	v_lshlrev_b64 v[114:115], 6, v[198:199]
	v_lshl_add_u64 v[114:115], s[12:13], 0, v[114:115]
	v_lshl_add_u64 v[114:115], s[18:19], 2, v[114:115]
	s_lshl_b32 s16, s36, 2
	v_lshl_add_u64 v[114:115], v[114:115], 0, s[16:17]
	global_store_dword v[114:115], v116, off

.LBB0_2599:
	ds_read_b128 v[82:85], v165
	ds_read_b128 v[86:89], v165 offset:1024
	ds_read_b128 v[90:93], v165 offset:2048
	ds_read_b128 v[94:97], v165 offset:3072
	ds_read_b128 v[146:149], v184
	ds_read_b128 v[150:153], v184 offset:1024
	ds_read_b128 v[180:183], v184 offset:2048
	ds_read_b128 v[194:197], v184 offset:3072
	s_add_u32 s12, s10, 0xfffc0080
	s_addc_u32 s13, s11, -1
	s_cmp_eq_u32 s84, 12
	s_cselect_b32 s15, s1, s13
	s_cselect_b32 s14, s3, s12
	s_cselect_b32 s13, s16, s45
	s_cselect_b32 s12, s17, s43
	v_lshl_add_u64 v[230:231], s[10:11], 0, v[170:171]
	s_add_i32 m0, s54, 0xc000
	ds_read_b128 v[198:201], v185
	ds_read_b128 v[202:205], v185 offset:1024
	ds_read_b128 v[206:209], v185 offset:2048
	ds_read_b128 v[210:213], v185 offset:3072
	ds_read_b128 v[214:217], v185 offset:4096
	ds_read_b128 v[218:221], v185 offset:5120
	ds_read_b128 v[222:225], v185 offset:6144
	ds_read_b128 v[226:229], v185 offset:7168
	global_load_lds_dwordx4 v[230:231], off
	v_lshl_add_u64 v[230:231], s[10:11], 0, v[172:173]
	s_add_i32 m0, s54, 0xe000
	s_nop 0
	global_load_lds_dwordx4 v[230:231], off
	s_waitcnt vmcnt(8)
	s_waitcnt lgkmcnt(0)
	s_barrier
	s_setprio 1
	v_mfma_f32_16x16x32_bf16 v[62:65], v[82:85], v[198:201], v[62:65]
	v_mfma_f32_16x16x32_bf16 v[58:61], v[90:93], v[198:201], v[58:61]
	v_mfma_f32_16x16x32_bf16 v[54:57], v[82:85], v[206:209], v[54:57]
	v_mfma_f32_16x16x32_bf16 v[50:53], v[90:93], v[206:209], v[50:53]
	v_mfma_f32_16x16x32_bf16 v[46:49], v[82:85], v[214:217], v[46:49]
	v_mfma_f32_16x16x32_bf16 v[42:45], v[90:93], v[214:217], v[42:45]
	v_mfma_f32_16x16x32_bf16 v[38:41], v[82:85], v[222:225], v[38:41]
	v_mfma_f32_16x16x32_bf16 v[34:37], v[90:93], v[222:225], v[34:37]
	v_mfma_f32_16x16x32_bf16 v[62:65], v[86:89], v[202:205], v[62:65]
	v_mfma_f32_16x16x32_bf16 v[58:61], v[94:97], v[202:205], v[58:61]
	v_mfma_f32_16x16x32_bf16 v[54:57], v[86:89], v[210:213], v[54:57]
	v_mfma_f32_16x16x32_bf16 v[50:53], v[94:97], v[210:213], v[50:53]
	v_mfma_f32_16x16x32_bf16 v[46:49], v[86:89], v[218:221], v[46:49]
	v_mfma_f32_16x16x32_bf16 v[42:45], v[94:97], v[218:221], v[42:45]
	v_mfma_f32_16x16x32_bf16 v[38:41], v[86:89], v[226:229], v[38:41]
	v_mfma_f32_16x16x32_bf16 v[34:37], v[94:97], v[226:229], v[34:37]
	v_mfma_f32_16x16x32_bf16 v[142:145], v[146:149], v[198:201], v[142:145]
	v_mfma_f32_16x16x32_bf16 v[138:141], v[180:183], v[198:201], v[138:141]
	v_mfma_f32_16x16x32_bf16 v[134:137], v[146:149], v[206:209], v[134:137]
	v_mfma_f32_16x16x32_bf16 v[130:133], v[180:183], v[206:209], v[130:133]
	v_mfma_f32_16x16x32_bf16 v[126:129], v[146:149], v[214:217], v[126:129]
	v_mfma_f32_16x16x32_bf16 v[122:125], v[180:183], v[214:217], v[122:125]
	v_mfma_f32_16x16x32_bf16 v[118:121], v[146:149], v[222:225], v[118:121]
	v_mfma_f32_16x16x32_bf16 v[114:117], v[180:183], v[222:225], v[114:117]
	v_mfma_f32_16x16x32_bf16 v[142:145], v[150:153], v[202:205], v[142:145]
	v_mfma_f32_16x16x32_bf16 v[138:141], v[194:197], v[202:205], v[138:141]
	v_mfma_f32_16x16x32_bf16 v[134:137], v[150:153], v[210:213], v[134:137]
	v_mfma_f32_16x16x32_bf16 v[130:133], v[194:197], v[210:213], v[130:133]
	v_mfma_f32_16x16x32_bf16 v[126:129], v[150:153], v[218:221], v[126:129]
	v_mfma_f32_16x16x32_bf16 v[122:125], v[194:197], v[218:221], v[122:125]
	v_mfma_f32_16x16x32_bf16 v[118:121], v[150:153], v[226:229], v[118:121]
	v_mfma_f32_16x16x32_bf16 v[114:117], v[194:197], v[226:229], v[114:117]
	s_setprio 0
	s_barrier
	s_add_i32 s85, s68, s53
	v_lshl_add_u64 v[230:231], s[12:13], 0, v[156:157]
	s_mov_b32 m0, s85
	ds_read_b128 v[198:201], v185 offset:16384
	ds_read_b128 v[202:205], v185 offset:17408
	ds_read_b128 v[206:209], v185 offset:18432
	ds_read_b128 v[210:213], v185 offset:19456
	ds_read_b128 v[214:217], v185 offset:20480
	ds_read_b128 v[218:221], v185 offset:21504
	ds_read_b128 v[222:225], v185 offset:22528
	ds_read_b128 v[226:229], v185 offset:23552
	global_load_lds_dwordx4 v[230:231], off
	s_add_i32 m0, s85, 0x2000
	s_add_u32 s86, s12, 0x40000
	v_lshl_add_u64 v[232:233], s[12:13], 0, v[160:161]
	s_addc_u32 s87, s13, 0
	s_add_i32 s85, s69, s53
	global_load_lds_dwordx4 v[232:233], off
	v_lshl_add_u64 v[234:235], s[86:87], 0, v[156:157]
	s_mov_b32 m0, s85
	v_lshl_add_u64 v[236:237], s[14:15], 0, v[158:159]
	global_load_lds_dwordx4 v[234:235], off
	v_lshl_add_u64 v[234:235], s[86:87], 0, v[160:161]
	s_add_i32 m0, s85, 0x2000
	s_nop 0
	global_load_lds_dwordx4 v[234:235], off
	v_lshl_add_u64 v[234:235], s[14:15], 0, v[154:155]
	s_mov_b32 m0, s54
	s_nop 0
	global_load_lds_dwordx4 v[234:235], off
	s_mov_b32 m0, s55
	s_nop 0
	global_load_lds_dwordx4 v[236:237], off
	s_waitcnt vmcnt(8)
	s_waitcnt lgkmcnt(0)
	s_barrier
	s_setprio 1
	v_mfma_f32_16x16x32_bf16 v[30:33], v[82:85], v[198:201], v[30:33]
	v_mfma_f32_16x16x32_bf16 v[26:29], v[90:93], v[198:201], v[26:29]
	v_mfma_f32_16x16x32_bf16 v[22:25], v[82:85], v[206:209], v[22:25]
	v_mfma_f32_16x16x32_bf16 v[18:21], v[90:93], v[206:209], v[18:21]
	v_mfma_f32_16x16x32_bf16 v[14:17], v[82:85], v[214:217], v[14:17]
	v_mfma_f32_16x16x32_bf16 v[10:13], v[90:93], v[214:217], v[10:13]
	v_mfma_f32_16x16x32_bf16 v[6:9], v[82:85], v[222:225], v[6:9]
	v_mfma_f32_16x16x32_bf16 v[2:5], v[90:93], v[222:225], v[2:5]
	v_mfma_f32_16x16x32_bf16 v[30:33], v[86:89], v[202:205], v[30:33]
	v_mfma_f32_16x16x32_bf16 v[26:29], v[94:97], v[202:205], v[26:29]
	v_mfma_f32_16x16x32_bf16 v[22:25], v[86:89], v[210:213], v[22:25]
	v_mfma_f32_16x16x32_bf16 v[18:21], v[94:97], v[210:213], v[18:21]
	v_mfma_f32_16x16x32_bf16 v[14:17], v[86:89], v[218:221], v[14:17]
	v_mfma_f32_16x16x32_bf16 v[10:13], v[94:97], v[218:221], v[10:13]
	v_mfma_f32_16x16x32_bf16 v[6:9], v[86:89], v[226:229], v[6:9]
	v_mfma_f32_16x16x32_bf16 v[2:5], v[94:97], v[226:229], v[2:5]
	v_mfma_f32_16x16x32_bf16 v[78:81], v[146:149], v[214:217], v[78:81]
	v_mfma_f32_16x16x32_bf16 v[74:77], v[180:183], v[214:217], v[74:77]
	v_mfma_f32_16x16x32_bf16 v[70:73], v[146:149], v[222:225], v[70:73]
	v_mfma_f32_16x16x32_bf16 v[66:69], v[180:183], v[222:225], v[66:69]
	v_mfma_f32_16x16x32_bf16 v[82:85], v[146:149], v[198:201], v[110:113]
	v_mfma_f32_16x16x32_bf16 v[86:89], v[180:183], v[198:201], v[106:109]
	v_mfma_f32_16x16x32_bf16 v[90:93], v[146:149], v[206:209], v[102:105]
	v_mfma_f32_16x16x32_bf16 v[94:97], v[180:183], v[206:209], v[98:101]
	v_mfma_f32_16x16x32_bf16 v[78:81], v[150:153], v[218:221], v[78:81]
	v_mfma_f32_16x16x32_bf16 v[74:77], v[194:197], v[218:221], v[74:77]
	v_mfma_f32_16x16x32_bf16 v[70:73], v[150:153], v[226:229], v[70:73]
	v_mfma_f32_16x16x32_bf16 v[66:69], v[194:197], v[226:229], v[66:69]
	v_mfma_f32_16x16x32_bf16 v[82:85], v[150:153], v[202:205], v[82:85]
	v_mfma_f32_16x16x32_bf16 v[86:89], v[194:197], v[202:205], v[86:89]
	v_mfma_f32_16x16x32_bf16 v[90:93], v[150:153], v[210:213], v[90:93]
	v_mfma_f32_16x16x32_bf16 v[94:97], v[194:197], v[210:213], v[94:97]
	s_setprio 0
	s_barrier
	ds_read_b128 v[98:101], v189
	ds_read_b128 v[102:105], v189 offset:1024
	ds_read_b128 v[106:109], v189 offset:2048
	ds_read_b128 v[110:113], v189 offset:3072
	ds_read_b128 v[146:149], v190
	ds_read_b128 v[150:153], v190 offset:1024
	ds_read_b128 v[180:183], v190 offset:2048
	ds_read_b128 v[194:197], v190 offset:3072
	s_add_u32 s14, s14, 0x40000
	s_addc_u32 s15, s15, 0
	s_mov_b32 m0, s56
	v_lshl_add_u64 v[238:239], s[14:15], 0, v[154:155]
	ds_read_b128 v[198:201], v185 offset:32768
	ds_read_b128 v[202:205], v185 offset:33792
	ds_read_b128 v[206:209], v185 offset:34816
	ds_read_b128 v[210:213], v185 offset:35840
	ds_read_b128 v[214:217], v185 offset:36864
	ds_read_b128 v[218:221], v185 offset:37888
	ds_read_b128 v[222:225], v185 offset:38912
	ds_read_b128 v[226:229], v185 offset:39936
	global_load_lds_dwordx4 v[238:239], off
	v_lshl_add_u64 v[238:239], s[14:15], 0, v[158:159]
	s_mov_b32 m0, s57
	s_nop 0
	global_load_lds_dwordx4 v[238:239], off
	s_waitcnt vmcnt(8)
	s_waitcnt lgkmcnt(0)
	s_barrier
	s_setprio 1
	v_mfma_f32_16x16x32_bf16 v[62:65], v[98:101], v[198:201], v[62:65]
	v_mfma_f32_16x16x32_bf16 v[58:61], v[106:109], v[198:201], v[58:61]
	v_mfma_f32_16x16x32_bf16 v[54:57], v[98:101], v[206:209], v[54:57]
	v_mfma_f32_16x16x32_bf16 v[50:53], v[106:109], v[206:209], v[50:53]
	v_mfma_f32_16x16x32_bf16 v[46:49], v[98:101], v[214:217], v[46:49]
	v_mfma_f32_16x16x32_bf16 v[42:45], v[106:109], v[214:217], v[42:45]
	v_mfma_f32_16x16x32_bf16 v[38:41], v[98:101], v[222:225], v[38:41]
	v_mfma_f32_16x16x32_bf16 v[34:37], v[106:109], v[222:225], v[34:37]
	v_mfma_f32_16x16x32_bf16 v[62:65], v[102:105], v[202:205], v[62:65]
	v_mfma_f32_16x16x32_bf16 v[58:61], v[110:113], v[202:205], v[58:61]
	v_mfma_f32_16x16x32_bf16 v[54:57], v[102:105], v[210:213], v[54:57]
	v_mfma_f32_16x16x32_bf16 v[50:53], v[110:113], v[210:213], v[50:53]
	v_mfma_f32_16x16x32_bf16 v[46:49], v[102:105], v[218:221], v[46:49]
	v_mfma_f32_16x16x32_bf16 v[42:45], v[110:113], v[218:221], v[42:45]
	v_mfma_f32_16x16x32_bf16 v[38:41], v[102:105], v[226:229], v[38:41]
	v_mfma_f32_16x16x32_bf16 v[34:37], v[110:113], v[226:229], v[34:37]
	v_mfma_f32_16x16x32_bf16 v[142:145], v[146:149], v[198:201], v[142:145]
	v_mfma_f32_16x16x32_bf16 v[138:141], v[180:183], v[198:201], v[138:141]
	v_mfma_f32_16x16x32_bf16 v[134:137], v[146:149], v[206:209], v[134:137]
	v_mfma_f32_16x16x32_bf16 v[130:133], v[180:183], v[206:209], v[130:133]
	v_mfma_f32_16x16x32_bf16 v[126:129], v[146:149], v[214:217], v[126:129]
	v_mfma_f32_16x16x32_bf16 v[122:125], v[180:183], v[214:217], v[122:125]
	v_mfma_f32_16x16x32_bf16 v[118:121], v[146:149], v[222:225], v[118:121]
	v_mfma_f32_16x16x32_bf16 v[114:117], v[180:183], v[222:225], v[114:117]
	v_mfma_f32_16x16x32_bf16 v[142:145], v[150:153], v[202:205], v[142:145]
	v_mfma_f32_16x16x32_bf16 v[138:141], v[194:197], v[202:205], v[138:141]
	v_mfma_f32_16x16x32_bf16 v[134:137], v[150:153], v[210:213], v[134:137]
	v_mfma_f32_16x16x32_bf16 v[130:133], v[194:197], v[210:213], v[130:133]
	v_mfma_f32_16x16x32_bf16 v[126:129], v[150:153], v[218:221], v[126:129]
	v_mfma_f32_16x16x32_bf16 v[122:125], v[194:197], v[218:221], v[122:125]
	v_mfma_f32_16x16x32_bf16 v[118:121], v[150:153], v[226:229], v[118:121]
	v_mfma_f32_16x16x32_bf16 v[114:117], v[194:197], v[226:229], v[114:117]
	s_setprio 0
	s_barrier
	s_add_i32 s14, s82, s53
	v_lshl_add_u64 v[230:231], v[230:231], 0, s[38:39]
	s_mov_b32 m0, s14
	ds_read_b128 v[198:201], v185 offset:49152
	ds_read_b128 v[202:205], v185 offset:50176
	ds_read_b128 v[206:209], v185 offset:51200
	ds_read_b128 v[210:213], v185 offset:52224
	ds_read_b128 v[214:217], v185 offset:53248
	ds_read_b128 v[218:221], v185 offset:54272
	ds_read_b128 v[222:225], v185 offset:55296
	ds_read_b128 v[226:229], v185 offset:56320
	global_load_lds_dwordx4 v[230:231], off
	s_add_i32 m0, s14, 0x2000
	s_add_u32 s12, s12, 0x40080
	v_lshl_add_u64 v[230:231], v[232:233], 0, s[38:39]
	s_addc_u32 s13, s13, 0
	s_add_i32 s14, s83, s53
	global_load_lds_dwordx4 v[230:231], off
	v_lshl_add_u64 v[230:231], s[12:13], 0, v[156:157]
	s_mov_b32 m0, s14
	s_nop 0
	global_load_lds_dwordx4 v[230:231], off
	v_lshl_add_u64 v[230:231], s[12:13], 0, v[160:161]
	s_add_i32 m0, s14, 0x2000
	s_nop 0
	global_load_lds_dwordx4 v[230:231], off
	v_lshl_add_u64 v[230:231], v[234:235], 0, s[38:39]
	s_mov_b32 m0, s62
	s_nop 0
	global_load_lds_dwordx4 v[230:231], off
	v_lshl_add_u64 v[230:231], v[236:237], 0, s[38:39]
	s_mov_b32 m0, s63
	s_nop 0
	global_load_lds_dwordx4 v[230:231], off
	s_waitcnt vmcnt(8)
	s_waitcnt lgkmcnt(0)
	s_barrier
	s_setprio 1
	v_mfma_f32_16x16x32_bf16 v[30:33], v[98:101], v[198:201], v[30:33]
	v_mfma_f32_16x16x32_bf16 v[26:29], v[106:109], v[198:201], v[26:29]
	v_mfma_f32_16x16x32_bf16 v[22:25], v[98:101], v[206:209], v[22:25]
	v_mfma_f32_16x16x32_bf16 v[18:21], v[106:109], v[206:209], v[18:21]
	v_mfma_f32_16x16x32_bf16 v[14:17], v[98:101], v[214:217], v[14:17]
	v_mfma_f32_16x16x32_bf16 v[10:13], v[106:109], v[214:217], v[10:13]
	v_mfma_f32_16x16x32_bf16 v[6:9], v[98:101], v[222:225], v[6:9]
	v_mfma_f32_16x16x32_bf16 v[2:5], v[106:109], v[222:225], v[2:5]
	v_mfma_f32_16x16x32_bf16 v[30:33], v[102:105], v[202:205], v[30:33]
	v_mfma_f32_16x16x32_bf16 v[26:29], v[110:113], v[202:205], v[26:29]
	v_mfma_f32_16x16x32_bf16 v[22:25], v[102:105], v[210:213], v[22:25]
	v_mfma_f32_16x16x32_bf16 v[18:21], v[110:113], v[210:213], v[18:21]
	v_mfma_f32_16x16x32_bf16 v[14:17], v[102:105], v[218:221], v[14:17]
	v_mfma_f32_16x16x32_bf16 v[10:13], v[110:113], v[218:221], v[10:13]
	v_mfma_f32_16x16x32_bf16 v[6:9], v[102:105], v[226:229], v[6:9]
	v_mfma_f32_16x16x32_bf16 v[2:5], v[110:113], v[226:229], v[2:5]
	v_mfma_f32_16x16x32_bf16 v[82:85], v[146:149], v[198:201], v[82:85]
	v_mfma_f32_16x16x32_bf16 v[110:113], v[150:153], v[202:205], v[82:85]
	v_mfma_f32_16x16x32_bf16 v[82:85], v[180:183], v[198:201], v[86:89]
	v_mfma_f32_16x16x32_bf16 v[106:109], v[194:197], v[202:205], v[82:85]
	v_mfma_f32_16x16x32_bf16 v[82:85], v[146:149], v[206:209], v[90:93]
	v_mfma_f32_16x16x32_bf16 v[102:105], v[150:153], v[210:213], v[82:85]
	v_mfma_f32_16x16x32_bf16 v[82:85], v[180:183], v[206:209], v[94:97]
	v_mfma_f32_16x16x32_bf16 v[78:81], v[146:149], v[214:217], v[78:81]
	v_mfma_f32_16x16x32_bf16 v[74:77], v[180:183], v[214:217], v[74:77]
	v_mfma_f32_16x16x32_bf16 v[70:73], v[146:149], v[222:225], v[70:73]
	v_mfma_f32_16x16x32_bf16 v[66:69], v[180:183], v[222:225], v[66:69]
	v_mfma_f32_16x16x32_bf16 v[98:101], v[194:197], v[210:213], v[82:85]
	v_mfma_f32_16x16x32_bf16 v[78:81], v[150:153], v[218:221], v[78:81]
	v_mfma_f32_16x16x32_bf16 v[74:77], v[194:197], v[218:221], v[74:77]
	v_mfma_f32_16x16x32_bf16 v[70:73], v[150:153], v[226:229], v[70:73]
	v_mfma_f32_16x16x32_bf16 v[66:69], v[194:197], v[226:229], v[66:69]
	s_setprio 0
	s_barrier
	s_add_i32 s84, s84, 2
	s_add_u32 s10, s10, 0x100
	s_addc_u32 s11, s11, 0
	s_add_u32 s43, s43, 0x100
	s_addc_u32 s45, s45, 0
	s_cmp_gt_u32 s84, 13
	s_cbranch_scc0 .LBB0_2599
	s_and_b64 vcc, exec, s[40:41]
	s_cbranch_vccz .LBB0_2602
	s_barrier

.LBB0_4727:
	ds_read_b128 v[146:149], v159
	ds_read_b128 v[150:153], v159 offset:1024
	ds_read_b128 v[154:157], v159 offset:2048
	ds_read_b128 v[164:167], v159 offset:3072
	ds_read_b128 v[168:171], v160
	ds_read_b128 v[172:175], v160 offset:1024
	ds_read_b128 v[176:179], v160 offset:2048
	ds_read_b128 v[180:183], v160 offset:3072
	s_add_u32 s20, s18, 0xfff50080
	s_addc_u32 s21, s19, -1
	s_cmp_eq_u32 s51, 40
	s_cselect_b32 s23, s7, s21
	s_cselect_b32 s22, s6, s20
	s_cselect_b32 s21, s9, s50
	s_cselect_b32 s20, s8, s49
	v_lshl_add_u64 v[216:217], s[18:19], 0, v[138:139]
	s_add_i32 m0, s31, 0xc000
	ds_read_b128 v[184:187], v161
	ds_read_b128 v[188:191], v161 offset:1024
	ds_read_b128 v[192:195], v161 offset:2048
	ds_read_b128 v[196:199], v161 offset:3072
	ds_read_b128 v[200:203], v161 offset:4096
	ds_read_b128 v[204:207], v161 offset:5120
	ds_read_b128 v[208:211], v161 offset:6144
	ds_read_b128 v[212:215], v161 offset:7168
	global_load_lds_dwordx4 v[216:217], off
	v_lshl_add_u64 v[216:217], s[18:19], 0, v[140:141]
	s_add_i32 m0, s31, 0xe000
	s_nop 0
	global_load_lds_dwordx4 v[216:217], off
	s_waitcnt vmcnt(8)
	s_waitcnt lgkmcnt(0)
	s_barrier
	s_setprio 1
	v_mfma_f32_16x16x32_bf16 v[126:129], v[146:149], v[184:187], v[126:129]
	v_mfma_f32_16x16x32_bf16 v[122:125], v[154:157], v[184:187], v[122:125]
	v_mfma_f32_16x16x32_bf16 v[118:121], v[146:149], v[192:195], v[118:121]
	v_mfma_f32_16x16x32_bf16 v[114:117], v[154:157], v[192:195], v[114:117]
	v_mfma_f32_16x16x32_bf16 v[106:109], v[146:149], v[200:203], v[106:109]
	v_mfma_f32_16x16x32_bf16 v[98:101], v[154:157], v[200:203], v[98:101]
	v_mfma_f32_16x16x32_bf16 v[90:93], v[146:149], v[208:211], v[90:93]
	v_mfma_f32_16x16x32_bf16 v[82:85], v[154:157], v[208:211], v[82:85]
	v_mfma_f32_16x16x32_bf16 v[126:129], v[150:153], v[188:191], v[126:129]
	v_mfma_f32_16x16x32_bf16 v[122:125], v[164:167], v[188:191], v[122:125]
	v_mfma_f32_16x16x32_bf16 v[118:121], v[150:153], v[196:199], v[118:121]
	v_mfma_f32_16x16x32_bf16 v[114:117], v[164:167], v[196:199], v[114:117]
	v_mfma_f32_16x16x32_bf16 v[106:109], v[150:153], v[204:207], v[106:109]
	v_mfma_f32_16x16x32_bf16 v[98:101], v[164:167], v[204:207], v[98:101]
	v_mfma_f32_16x16x32_bf16 v[90:93], v[150:153], v[212:215], v[90:93]
	v_mfma_f32_16x16x32_bf16 v[82:85], v[164:167], v[212:215], v[82:85]
	v_mfma_f32_16x16x32_bf16 v[110:113], v[168:171], v[184:187], v[110:113]
	v_mfma_f32_16x16x32_bf16 v[102:105], v[176:179], v[184:187], v[102:105]
	v_mfma_f32_16x16x32_bf16 v[94:97], v[168:171], v[192:195], v[94:97]
	v_mfma_f32_16x16x32_bf16 v[86:89], v[176:179], v[192:195], v[86:89]
	v_mfma_f32_16x16x32_bf16 v[78:81], v[168:171], v[200:203], v[78:81]
	v_mfma_f32_16x16x32_bf16 v[74:77], v[176:179], v[200:203], v[74:77]
	v_mfma_f32_16x16x32_bf16 v[70:73], v[168:171], v[208:211], v[70:73]
	v_mfma_f32_16x16x32_bf16 v[66:69], v[176:179], v[208:211], v[66:69]
	v_mfma_f32_16x16x32_bf16 v[110:113], v[172:175], v[188:191], v[110:113]
	v_mfma_f32_16x16x32_bf16 v[102:105], v[180:183], v[188:191], v[102:105]
	v_mfma_f32_16x16x32_bf16 v[94:97], v[172:175], v[196:199], v[94:97]
	v_mfma_f32_16x16x32_bf16 v[86:89], v[180:183], v[196:199], v[86:89]
	v_mfma_f32_16x16x32_bf16 v[78:81], v[172:175], v[204:207], v[78:81]
	v_mfma_f32_16x16x32_bf16 v[74:77], v[180:183], v[204:207], v[74:77]
	v_mfma_f32_16x16x32_bf16 v[70:73], v[172:175], v[212:215], v[70:73]
	v_mfma_f32_16x16x32_bf16 v[66:69], v[180:183], v[212:215], v[66:69]
	s_setprio 0
	s_barrier
	s_add_i32 s52, s41, s30
	v_lshl_add_u64 v[216:217], s[20:21], 0, v[132:133]
	s_mov_b32 m0, s52
	ds_read_b128 v[184:187], v161 offset:16384
	ds_read_b128 v[188:191], v161 offset:17408
	ds_read_b128 v[192:195], v161 offset:18432
	ds_read_b128 v[196:199], v161 offset:19456
	ds_read_b128 v[200:203], v161 offset:20480
	ds_read_b128 v[204:207], v161 offset:21504
	ds_read_b128 v[208:211], v161 offset:22528
	ds_read_b128 v[212:215], v161 offset:23552
	global_load_lds_dwordx4 v[216:217], off
	s_add_i32 m0, s52, 0x2000
	s_add_u32 s52, s20, 0xb0000
	v_lshl_add_u64 v[218:219], s[20:21], 0, v[136:137]
	s_addc_u32 s53, s21, 0
	s_add_i32 s54, s42, s30
	global_load_lds_dwordx4 v[218:219], off
	v_lshl_add_u64 v[220:221], s[52:53], 0, v[132:133]
	s_mov_b32 m0, s54
	v_lshl_add_u64 v[222:223], s[22:23], 0, v[134:135]
	global_load_lds_dwordx4 v[220:221], off
	v_lshl_add_u64 v[220:221], s[52:53], 0, v[136:137]
	s_add_i32 m0, s54, 0x2000
	s_nop 0
	global_load_lds_dwordx4 v[220:221], off
	v_lshl_add_u64 v[220:221], s[22:23], 0, v[130:131]
	s_mov_b32 m0, s31
	s_nop 0
	global_load_lds_dwordx4 v[220:221], off
	s_mov_b32 m0, s33
	s_nop 0
	global_load_lds_dwordx4 v[222:223], off
	s_waitcnt vmcnt(8)
	s_waitcnt lgkmcnt(0)
	s_barrier
	s_setprio 1
	v_mfma_f32_16x16x32_bf16 v[62:65], v[146:149], v[184:187], v[62:65]
	v_mfma_f32_16x16x32_bf16 v[58:61], v[154:157], v[184:187], v[58:61]
	v_mfma_f32_16x16x32_bf16 v[54:57], v[146:149], v[192:195], v[54:57]
	v_mfma_f32_16x16x32_bf16 v[46:49], v[154:157], v[192:195], v[46:49]
	v_mfma_f32_16x16x32_bf16 v[38:41], v[146:149], v[200:203], v[38:41]
	v_mfma_f32_16x16x32_bf16 v[30:33], v[154:157], v[200:203], v[30:33]
	v_mfma_f32_16x16x32_bf16 v[22:25], v[146:149], v[208:211], v[22:25]
	v_mfma_f32_16x16x32_bf16 v[14:17], v[154:157], v[208:211], v[14:17]
	v_mfma_f32_16x16x32_bf16 v[62:65], v[150:153], v[188:191], v[62:65]
	v_mfma_f32_16x16x32_bf16 v[58:61], v[164:167], v[188:191], v[58:61]
	v_mfma_f32_16x16x32_bf16 v[54:57], v[150:153], v[196:199], v[54:57]
	v_mfma_f32_16x16x32_bf16 v[46:49], v[164:167], v[196:199], v[46:49]
	v_mfma_f32_16x16x32_bf16 v[38:41], v[150:153], v[204:207], v[38:41]
	v_mfma_f32_16x16x32_bf16 v[30:33], v[164:167], v[204:207], v[30:33]
	v_mfma_f32_16x16x32_bf16 v[22:25], v[150:153], v[212:215], v[22:25]
	v_mfma_f32_16x16x32_bf16 v[14:17], v[164:167], v[212:215], v[14:17]
	v_mfma_f32_16x16x32_bf16 v[50:53], v[168:171], v[184:187], v[50:53]
	v_mfma_f32_16x16x32_bf16 v[42:45], v[176:179], v[184:187], v[42:45]
	v_mfma_f32_16x16x32_bf16 v[34:37], v[168:171], v[192:195], v[34:37]
	v_mfma_f32_16x16x32_bf16 v[26:29], v[176:179], v[192:195], v[26:29]
	v_mfma_f32_16x16x32_bf16 v[18:21], v[168:171], v[200:203], v[18:21]
	v_mfma_f32_16x16x32_bf16 v[10:13], v[176:179], v[200:203], v[10:13]
	v_mfma_f32_16x16x32_bf16 v[6:9], v[168:171], v[208:211], v[6:9]
	v_mfma_f32_16x16x32_bf16 v[2:5], v[176:179], v[208:211], v[2:5]
	v_mfma_f32_16x16x32_bf16 v[50:53], v[172:175], v[188:191], v[50:53]
	v_mfma_f32_16x16x32_bf16 v[42:45], v[180:183], v[188:191], v[42:45]
	v_mfma_f32_16x16x32_bf16 v[34:37], v[172:175], v[196:199], v[34:37]
	v_mfma_f32_16x16x32_bf16 v[26:29], v[180:183], v[196:199], v[26:29]
	v_mfma_f32_16x16x32_bf16 v[18:21], v[172:175], v[204:207], v[18:21]
	v_mfma_f32_16x16x32_bf16 v[10:13], v[180:183], v[204:207], v[10:13]
	v_mfma_f32_16x16x32_bf16 v[6:9], v[172:175], v[212:215], v[6:9]
	v_mfma_f32_16x16x32_bf16 v[2:5], v[180:183], v[212:215], v[2:5]
	s_setprio 0
	s_barrier
	ds_read_b128 v[146:149], v162
	ds_read_b128 v[150:153], v162 offset:1024
	ds_read_b128 v[154:157], v162 offset:2048
	ds_read_b128 v[164:167], v162 offset:3072
	ds_read_b128 v[168:171], v163
	ds_read_b128 v[172:175], v163 offset:1024
	ds_read_b128 v[176:179], v163 offset:2048
	ds_read_b128 v[180:183], v163 offset:3072
	s_add_u32 s22, s22, 0xb0000
	s_addc_u32 s23, s23, 0
	s_mov_b32 m0, s34
	v_lshl_add_u64 v[224:225], s[22:23], 0, v[130:131]
	ds_read_b128 v[184:187], v161 offset:32768
	ds_read_b128 v[188:191], v161 offset:33792
	ds_read_b128 v[192:195], v161 offset:34816
	ds_read_b128 v[196:199], v161 offset:35840
	ds_read_b128 v[200:203], v161 offset:36864
	ds_read_b128 v[204:207], v161 offset:37888
	ds_read_b128 v[208:211], v161 offset:38912
	ds_read_b128 v[212:215], v161 offset:39936
	global_load_lds_dwordx4 v[224:225], off
	v_lshl_add_u64 v[224:225], s[22:23], 0, v[134:135]
	s_mov_b32 m0, s35
	s_nop 0
	global_load_lds_dwordx4 v[224:225], off
	s_waitcnt vmcnt(8)
	s_waitcnt lgkmcnt(0)
	s_barrier
	s_setprio 1
	v_mfma_f32_16x16x32_bf16 v[126:129], v[146:149], v[184:187], v[126:129]
	v_mfma_f32_16x16x32_bf16 v[122:125], v[154:157], v[184:187], v[122:125]
	v_mfma_f32_16x16x32_bf16 v[118:121], v[146:149], v[192:195], v[118:121]
	v_mfma_f32_16x16x32_bf16 v[114:117], v[154:157], v[192:195], v[114:117]
	v_mfma_f32_16x16x32_bf16 v[106:109], v[146:149], v[200:203], v[106:109]
	v_mfma_f32_16x16x32_bf16 v[98:101], v[154:157], v[200:203], v[98:101]
	v_mfma_f32_16x16x32_bf16 v[90:93], v[146:149], v[208:211], v[90:93]
	v_mfma_f32_16x16x32_bf16 v[82:85], v[154:157], v[208:211], v[82:85]
	v_mfma_f32_16x16x32_bf16 v[126:129], v[150:153], v[188:191], v[126:129]
	v_mfma_f32_16x16x32_bf16 v[122:125], v[164:167], v[188:191], v[122:125]
	v_mfma_f32_16x16x32_bf16 v[118:121], v[150:153], v[196:199], v[118:121]
	v_mfma_f32_16x16x32_bf16 v[114:117], v[164:167], v[196:199], v[114:117]
	v_mfma_f32_16x16x32_bf16 v[106:109], v[150:153], v[204:207], v[106:109]
	v_mfma_f32_16x16x32_bf16 v[98:101], v[164:167], v[204:207], v[98:101]
	v_mfma_f32_16x16x32_bf16 v[90:93], v[150:153], v[212:215], v[90:93]
	v_mfma_f32_16x16x32_bf16 v[82:85], v[164:167], v[212:215], v[82:85]
	v_mfma_f32_16x16x32_bf16 v[110:113], v[168:171], v[184:187], v[110:113]
	v_mfma_f32_16x16x32_bf16 v[102:105], v[176:179], v[184:187], v[102:105]
	v_mfma_f32_16x16x32_bf16 v[94:97], v[168:171], v[192:195], v[94:97]
	v_mfma_f32_16x16x32_bf16 v[86:89], v[176:179], v[192:195], v[86:89]
	v_mfma_f32_16x16x32_bf16 v[78:81], v[168:171], v[200:203], v[78:81]
	v_mfma_f32_16x16x32_bf16 v[74:77], v[176:179], v[200:203], v[74:77]
	v_mfma_f32_16x16x32_bf16 v[70:73], v[168:171], v[208:211], v[70:73]
	v_mfma_f32_16x16x32_bf16 v[66:69], v[176:179], v[208:211], v[66:69]
	v_mfma_f32_16x16x32_bf16 v[110:113], v[172:175], v[188:191], v[110:113]
	v_mfma_f32_16x16x32_bf16 v[102:105], v[180:183], v[188:191], v[102:105]
	v_mfma_f32_16x16x32_bf16 v[94:97], v[172:175], v[196:199], v[94:97]
	v_mfma_f32_16x16x32_bf16 v[86:89], v[180:183], v[196:199], v[86:89]
	v_mfma_f32_16x16x32_bf16 v[78:81], v[172:175], v[204:207], v[78:81]
	v_mfma_f32_16x16x32_bf16 v[74:77], v[180:183], v[204:207], v[74:77]
	v_mfma_f32_16x16x32_bf16 v[70:73], v[172:175], v[212:215], v[70:73]
	v_mfma_f32_16x16x32_bf16 v[66:69], v[180:183], v[212:215], v[66:69]
	s_setprio 0
	s_barrier
	s_add_i32 s22, s43, s30
	v_lshl_add_u64 v[216:217], v[216:217], 0, s[10:11]
	s_mov_b32 m0, s22
	ds_read_b128 v[184:187], v161 offset:49152
	ds_read_b128 v[188:191], v161 offset:50176
	ds_read_b128 v[192:195], v161 offset:51200
	ds_read_b128 v[196:199], v161 offset:52224
	ds_read_b128 v[200:203], v161 offset:53248
	ds_read_b128 v[204:207], v161 offset:54272
	ds_read_b128 v[208:211], v161 offset:55296
	ds_read_b128 v[212:215], v161 offset:56320
	global_load_lds_dwordx4 v[216:217], off
	s_add_i32 m0, s22, 0x2000
	s_add_u32 s20, s20, 0xb0080
	v_lshl_add_u64 v[216:217], v[218:219], 0, s[10:11]
	s_addc_u32 s21, s21, 0
	s_add_i32 s22, s44, s30
	global_load_lds_dwordx4 v[216:217], off
	v_lshl_add_u64 v[216:217], s[20:21], 0, v[132:133]
	s_mov_b32 m0, s22
	s_nop 0
	global_load_lds_dwordx4 v[216:217], off
	v_lshl_add_u64 v[216:217], s[20:21], 0, v[136:137]
	s_add_i32 m0, s22, 0x2000
	s_nop 0
	global_load_lds_dwordx4 v[216:217], off
	v_lshl_add_u64 v[216:217], v[220:221], 0, s[10:11]
	s_mov_b32 m0, s37
	s_nop 0
	global_load_lds_dwordx4 v[216:217], off
	v_lshl_add_u64 v[216:217], v[222:223], 0, s[10:11]
	s_mov_b32 m0, s38
	s_nop 0
	global_load_lds_dwordx4 v[216:217], off
	s_waitcnt vmcnt(8)
	s_waitcnt lgkmcnt(0)
	s_barrier
	s_setprio 1
	v_mfma_f32_16x16x32_bf16 v[62:65], v[146:149], v[184:187], v[62:65]
	v_mfma_f32_16x16x32_bf16 v[58:61], v[154:157], v[184:187], v[58:61]
	v_mfma_f32_16x16x32_bf16 v[54:57], v[146:149], v[192:195], v[54:57]
	v_mfma_f32_16x16x32_bf16 v[46:49], v[154:157], v[192:195], v[46:49]
	v_mfma_f32_16x16x32_bf16 v[38:41], v[146:149], v[200:203], v[38:41]
	v_mfma_f32_16x16x32_bf16 v[30:33], v[154:157], v[200:203], v[30:33]
	v_mfma_f32_16x16x32_bf16 v[22:25], v[146:149], v[208:211], v[22:25]
	v_mfma_f32_16x16x32_bf16 v[14:17], v[154:157], v[208:211], v[14:17]
	v_mfma_f32_16x16x32_bf16 v[62:65], v[150:153], v[188:191], v[62:65]
	v_mfma_f32_16x16x32_bf16 v[58:61], v[164:167], v[188:191], v[58:61]
	v_mfma_f32_16x16x32_bf16 v[54:57], v[150:153], v[196:199], v[54:57]
	v_mfma_f32_16x16x32_bf16 v[46:49], v[164:167], v[196:199], v[46:49]
	v_mfma_f32_16x16x32_bf16 v[38:41], v[150:153], v[204:207], v[38:41]
	v_mfma_f32_16x16x32_bf16 v[30:33], v[164:167], v[204:207], v[30:33]
	v_mfma_f32_16x16x32_bf16 v[22:25], v[150:153], v[212:215], v[22:25]
	v_mfma_f32_16x16x32_bf16 v[14:17], v[164:167], v[212:215], v[14:17]
	v_mfma_f32_16x16x32_bf16 v[50:53], v[168:171], v[184:187], v[50:53]
	v_mfma_f32_16x16x32_bf16 v[42:45], v[176:179], v[184:187], v[42:45]
	v_mfma_f32_16x16x32_bf16 v[34:37], v[168:171], v[192:195], v[34:37]
	v_mfma_f32_16x16x32_bf16 v[26:29], v[176:179], v[192:195], v[26:29]
	v_mfma_f32_16x16x32_bf16 v[18:21], v[168:171], v[200:203], v[18:21]
	v_mfma_f32_16x16x32_bf16 v[10:13], v[176:179], v[200:203], v[10:13]
	v_mfma_f32_16x16x32_bf16 v[6:9], v[168:171], v[208:211], v[6:9]
	v_mfma_f32_16x16x32_bf16 v[2:5], v[176:179], v[208:211], v[2:5]
	v_mfma_f32_16x16x32_bf16 v[50:53], v[172:175], v[188:191], v[50:53]
	v_mfma_f32_16x16x32_bf16 v[42:45], v[180:183], v[188:191], v[42:45]
	v_mfma_f32_16x16x32_bf16 v[34:37], v[172:175], v[196:199], v[34:37]
	v_mfma_f32_16x16x32_bf16 v[26:29], v[180:183], v[196:199], v[26:29]
	v_mfma_f32_16x16x32_bf16 v[18:21], v[172:175], v[204:207], v[18:21]
	v_mfma_f32_16x16x32_bf16 v[10:13], v[180:183], v[204:207], v[10:13]
	v_mfma_f32_16x16x32_bf16 v[6:9], v[172:175], v[212:215], v[6:9]
	v_mfma_f32_16x16x32_bf16 v[2:5], v[180:183], v[212:215], v[2:5]
	s_setprio 0
	s_barrier
	s_add_i32 s51, s51, 2
	s_add_u32 s18, s18, 0x100
	s_addc_u32 s19, s19, 0
	s_add_u32 s49, s49, 0x100
	s_addc_u32 s50, s50, 0
	s_cmp_gt_u32 s51, 41
	s_cbranch_scc0 .LBB0_4727
	v_lshl_or_b32 v146, s48, 8, v158
	v_lshl_add_u32 v156, s47, 8, v1
	v_ashrrev_i32_e32 v147, 31, v146
	v_lshlrev_b64 v[146:147], 2, v[146:147]
	v_ashrrev_i32_e32 v157, 31, v156
	v_lshl_add_u64 v[148:149], s[62:63], 0, v[146:147]
	v_lshlrev_b64 v[150:151], 12, v[156:157]
	v_or_b32_e32 v176, 16, v156
	v_lshl_add_u64 v[172:173], v[148:149], 0, v[150:151]
	v_ashrrev_i32_e32 v177, 31, v176
	global_load_dwordx4 v[152:155], v[172:173], off offset:16 nt
	global_load_dwordx4 v[164:167], v[172:173], off nt
	global_load_dwordx4 v[168:171], v[172:173], off offset:528 nt
	s_nop 0
	global_load_dwordx4 v[172:175], v[172:173], off offset:512 nt
	v_lshlrev_b64 v[224:225], 12, v[176:177]
	v_or_b32_e32 v192, 32, v156
	v_lshl_add_u64 v[188:189], v[148:149], 0, v[224:225]
	v_ashrrev_i32_e32 v193, 31, v192
	global_load_dwordx4 v[176:179], v[188:189], off offset:16 nt
	global_load_dwordx4 v[180:183], v[188:189], off nt
	global_load_dwordx4 v[184:187], v[188:189], off offset:528 nt
	s_nop 0
	global_load_dwordx4 v[188:191], v[188:189], off offset:512 nt
	v_lshlrev_b64 v[226:227], 12, v[192:193]
	v_or_b32_e32 v156, 48, v156
	v_lshl_add_u64 v[204:205], v[148:149], 0, v[226:227]
	v_ashrrev_i32_e32 v157, 31, v156
	global_load_dwordx4 v[192:195], v[204:205], off offset:16 nt
	global_load_dwordx4 v[196:199], v[204:205], off nt
	global_load_dwordx4 v[200:203], v[204:205], off offset:528 nt
	s_nop 0
	global_load_dwordx4 v[204:207], v[204:205], off offset:512 nt
	v_lshlrev_b64 v[156:157], 12, v[156:157]
	v_lshl_add_u64 v[220:221], v[148:149], 0, v[156:157]
	global_load_dwordx4 v[208:211], v[220:221], off offset:16 nt
	global_load_dwordx4 v[212:215], v[220:221], off nt
	global_load_dwordx4 v[216:219], v[220:221], off offset:528 nt
	s_nop 0
	global_load_dwordx4 v[220:223], v[220:221], off offset:512 nt
	s_and_b64 vcc, exec, s[4:5]
	s_mov_b32 s48, s45
	s_mov_b32 s47, s46
	s_mov_b64 s[20:21], s[8:9]
	s_mov_b64 s[18:19], s[6:7]
	s_waitcnt vmcnt(0)
	v_pk_fma_f32 v[122:123], v[122:123], 0.5, v[152:153] op_sel_hi:[1,0,1]
	v_lshl_add_u64 v[152:153], s[62:63], 0, v[150:151]
	v_pk_fma_f32 v[128:129], v[128:129], 0.5, v[166:167] op_sel_hi:[1,0,1]
	v_pk_fma_f32 v[126:127], v[126:127], 0.5, v[164:165] op_sel_hi:[1,0,1]
	v_lshl_add_u64 v[152:153], v[152:153], 0, v[146:147]
	v_pk_fma_f32 v[112:113], v[112:113], 0.5, v[174:175] op_sel_hi:[1,0,1]
	v_pk_fma_f32 v[110:111], v[110:111], 0.5, v[172:173] op_sel_hi:[1,0,1]
	v_pk_fma_f32 v[124:125], v[124:125], 0.5, v[154:155] op_sel_hi:[1,0,1]
	global_store_dwordx4 v[152:153], v[126:129], off nt
	global_store_dwordx4 v[152:153], v[122:125], off offset:16 nt
	v_pk_fma_f32 v[104:105], v[104:105], 0.5, v[170:171] op_sel_hi:[1,0,1]
	v_pk_fma_f32 v[102:103], v[102:103], 0.5, v[168:169] op_sel_hi:[1,0,1]
	global_store_dwordx4 v[152:153], v[110:113], off offset:512 nt
	global_store_dwordx4 v[152:153], v[102:105], off offset:528 nt
	v_pk_fma_f32 v[96:97], v[96:97], 0.5, v[190:191] op_sel_hi:[1,0,1]
	v_pk_fma_f32 v[110:111], v[114:115], 0.5, v[176:177] op_sel_hi:[1,0,1]
	v_lshl_add_u64 v[114:115], s[62:63], 0, v[224:225]
	v_pk_fma_f32 v[104:105], v[120:121], 0.5, v[182:183] op_sel_hi:[1,0,1]
	v_pk_fma_f32 v[102:103], v[118:119], 0.5, v[180:181] op_sel_hi:[1,0,1]
	v_lshl_add_u64 v[114:115], v[114:115], 0, v[146:147]
	v_pk_fma_f32 v[94:95], v[94:95], 0.5, v[188:189] op_sel_hi:[1,0,1]
	v_pk_fma_f32 v[112:113], v[116:117], 0.5, v[178:179] op_sel_hi:[1,0,1]
	global_store_dwordx4 v[114:115], v[102:105], off nt
	global_store_dwordx4 v[114:115], v[110:113], off offset:16 nt
	v_pk_fma_f32 v[88:89], v[88:89], 0.5, v[186:187] op_sel_hi:[1,0,1]
	v_pk_fma_f32 v[86:87], v[86:87], 0.5, v[184:185] op_sel_hi:[1,0,1]
	global_store_dwordx4 v[114:115], v[94:97], off offset:512 nt
	global_store_dwordx4 v[114:115], v[86:89], off offset:528 nt
	v_pk_fma_f32 v[80:81], v[80:81], 0.5, v[206:207] op_sel_hi:[1,0,1]
	v_pk_fma_f32 v[94:95], v[98:99], 0.5, v[192:193] op_sel_hi:[1,0,1]
	v_lshl_add_u64 v[98:99], s[62:63], 0, v[226:227]
	v_pk_fma_f32 v[88:89], v[108:109], 0.5, v[198:199] op_sel_hi:[1,0,1]
	v_pk_fma_f32 v[86:87], v[106:107], 0.5, v[196:197] op_sel_hi:[1,0,1]
	v_lshl_add_u64 v[98:99], v[98:99], 0, v[146:147]
	v_pk_fma_f32 v[78:79], v[78:79], 0.5, v[204:205] op_sel_hi:[1,0,1]
	v_pk_fma_f32 v[96:97], v[100:101], 0.5, v[194:195] op_sel_hi:[1,0,1]
	global_store_dwordx4 v[98:99], v[86:89], off nt
	global_store_dwordx4 v[98:99], v[94:97], off offset:16 nt
	v_pk_fma_f32 v[76:77], v[76:77], 0.5, v[202:203] op_sel_hi:[1,0,1]
	v_pk_fma_f32 v[74:75], v[74:75], 0.5, v[200:201] op_sel_hi:[1,0,1]
	global_store_dwordx4 v[98:99], v[78:81], off offset:512 nt
	global_store_dwordx4 v[98:99], v[74:77], off offset:528 nt
	v_pk_fma_f32 v[72:73], v[72:73], 0.5, v[222:223] op_sel_hi:[1,0,1]
	v_pk_fma_f32 v[78:79], v[82:83], 0.5, v[208:209] op_sel_hi:[1,0,1]
	v_lshl_add_u64 v[82:83], s[62:63], 0, v[156:157]
	v_pk_fma_f32 v[76:77], v[92:93], 0.5, v[214:215] op_sel_hi:[1,0,1]
	v_pk_fma_f32 v[74:75], v[90:91], 0.5, v[212:213] op_sel_hi:[1,0,1]
	v_lshl_add_u64 v[82:83], v[82:83], 0, v[146:147]
	v_pk_fma_f32 v[70:71], v[70:71], 0.5, v[220:221] op_sel_hi:[1,0,1]
	v_pk_fma_f32 v[66:67], v[66:67], 0.5, v[216:217] op_sel_hi:[1,0,1]
	v_lshl_add_u64 v[156:157], v[150:151], 0, s[12:13]
	v_pk_fma_f32 v[80:81], v[84:85], 0.5, v[210:211] op_sel_hi:[1,0,1]
	global_store_dwordx4 v[82:83], v[74:77], off nt
	global_store_dwordx4 v[82:83], v[78:81], off offset:16 nt
	v_pk_fma_f32 v[68:69], v[68:69], 0.5, v[218:219] op_sel_hi:[1,0,1]
	global_store_dwordx4 v[82:83], v[70:73], off offset:512 nt
	global_store_dwordx4 v[82:83], v[66:69], off offset:528 nt
	v_lshl_add_u64 v[154:155], v[150:151], 0, s[14:15]
	v_lshl_add_u64 v[152:153], v[150:151], 0, s[16:17]
	v_lshl_add_u64 v[66:67], v[148:149], 0, v[156:157]
	global_load_dwordx4 v[110:113], v[66:67], off offset:16 nt
	global_load_dwordx4 v[122:125], v[66:67], off nt
	global_load_dwordx4 v[94:97], v[66:67], off offset:528 nt
	global_load_dwordx4 v[102:105], v[66:67], off offset:512 nt
	v_lshl_add_u64 v[66:67], v[148:149], 0, v[154:155]
	global_load_dwordx4 v[90:93], v[66:67], off offset:16 nt
	global_load_dwordx4 v[98:101], v[66:67], off nt
	global_load_dwordx4 v[78:81], v[66:67], off offset:528 nt
	global_load_dwordx4 v[86:89], v[66:67], off offset:512 nt
	v_lshl_add_u64 v[70:71], v[148:149], 0, v[152:153]
	global_load_dwordx4 v[74:77], v[70:71], off offset:16 nt
	global_load_dwordx4 v[82:85], v[70:71], off nt
	global_load_dwordx4 v[66:69], v[70:71], off offset:528 nt
	s_nop 0
	global_load_dwordx4 v[70:73], v[70:71], off offset:512 nt
	v_lshl_add_u64 v[150:151], v[150:151], 0, s[2:3]
	v_lshl_add_u64 v[114:115], v[148:149], 0, v[150:151]
	global_load_dwordx4 v[118:121], v[114:115], off offset:16 nt
	global_load_dwordx4 v[126:129], v[114:115], off nt
	global_load_dwordx4 v[106:109], v[114:115], off offset:528 nt
	s_nop 0
	global_load_dwordx4 v[114:117], v[114:115], off offset:512 nt
	s_waitcnt vmcnt(15)
	v_pk_fma_f32 v[58:59], v[58:59], 0.5, v[110:111] op_sel_hi:[1,0,1]
	v_lshl_add_u64 v[110:111], s[62:63], 0, v[156:157]
	s_waitcnt vmcnt(14)
	v_pk_fma_f32 v[64:65], v[64:65], 0.5, v[124:125] op_sel_hi:[1,0,1]
	v_pk_fma_f32 v[62:63], v[62:63], 0.5, v[122:123] op_sel_hi:[1,0,1]
	v_lshl_add_u64 v[110:111], v[110:111], 0, v[146:147]
	s_waitcnt vmcnt(12)
	v_pk_fma_f32 v[52:53], v[52:53], 0.5, v[104:105] op_sel_hi:[1,0,1]
	v_pk_fma_f32 v[50:51], v[50:51], 0.5, v[102:103] op_sel_hi:[1,0,1]
	v_pk_fma_f32 v[60:61], v[60:61], 0.5, v[112:113] op_sel_hi:[1,0,1]
	global_store_dwordx4 v[110:111], v[62:65], off nt
	global_store_dwordx4 v[110:111], v[58:61], off offset:16 nt
	v_pk_fma_f32 v[44:45], v[44:45], 0.5, v[96:97] op_sel_hi:[1,0,1]
	v_pk_fma_f32 v[42:43], v[42:43], 0.5, v[94:95] op_sel_hi:[1,0,1]
	global_store_dwordx4 v[110:111], v[50:53], off offset:512 nt
	global_store_dwordx4 v[110:111], v[42:45], off offset:528 nt
	s_waitcnt vmcnt(12)
	v_pk_fma_f32 v[36:37], v[36:37], 0.5, v[88:89] op_sel_hi:[1,0,1]
	v_lshl_add_u64 v[50:51], s[62:63], 0, v[154:155]
	v_pk_fma_f32 v[44:45], v[56:57], 0.5, v[100:101] op_sel_hi:[1,0,1]
	v_pk_fma_f32 v[42:43], v[54:55], 0.5, v[98:99] op_sel_hi:[1,0,1]
	v_lshl_add_u64 v[50:51], v[50:51], 0, v[146:147]
	v_pk_fma_f32 v[34:35], v[34:35], 0.5, v[86:87] op_sel_hi:[1,0,1]
	v_pk_fma_f32 v[48:49], v[48:49], 0.5, v[92:93] op_sel_hi:[1,0,1]
	v_pk_fma_f32 v[46:47], v[46:47], 0.5, v[90:91] op_sel_hi:[1,0,1]
	global_store_dwordx4 v[50:51], v[42:45], off nt
	global_store_dwordx4 v[50:51], v[46:49], off offset:16 nt
	v_pk_fma_f32 v[28:29], v[28:29], 0.5, v[80:81] op_sel_hi:[1,0,1]
	v_pk_fma_f32 v[26:27], v[26:27], 0.5, v[78:79] op_sel_hi:[1,0,1]
	global_store_dwordx4 v[50:51], v[34:37], off offset:512 nt
	global_store_dwordx4 v[50:51], v[26:29], off offset:528 nt
	s_waitcnt vmcnt(12)
	v_pk_fma_f32 v[20:21], v[20:21], 0.5, v[72:73] op_sel_hi:[1,0,1]
	v_lshl_add_u64 v[34:35], s[62:63], 0, v[152:153]
	v_pk_fma_f32 v[28:29], v[40:41], 0.5, v[84:85] op_sel_hi:[1,0,1]
	v_pk_fma_f32 v[26:27], v[38:39], 0.5, v[82:83] op_sel_hi:[1,0,1]
	v_lshl_add_u64 v[34:35], v[34:35], 0, v[146:147]
	v_pk_fma_f32 v[18:19], v[18:19], 0.5, v[70:71] op_sel_hi:[1,0,1]
	v_pk_fma_f32 v[32:33], v[32:33], 0.5, v[76:77] op_sel_hi:[1,0,1]
	v_pk_fma_f32 v[30:31], v[30:31], 0.5, v[74:75] op_sel_hi:[1,0,1]
	global_store_dwordx4 v[34:35], v[26:29], off nt
	global_store_dwordx4 v[34:35], v[30:33], off offset:16 nt
	v_pk_fma_f32 v[12:13], v[12:13], 0.5, v[68:69] op_sel_hi:[1,0,1]
	v_pk_fma_f32 v[10:11], v[10:11], 0.5, v[66:67] op_sel_hi:[1,0,1]
	global_store_dwordx4 v[34:35], v[18:21], off offset:512 nt
	global_store_dwordx4 v[34:35], v[10:13], off offset:528 nt
	s_waitcnt vmcnt(12)
	v_pk_fma_f32 v[8:9], v[8:9], 0.5, v[116:117] op_sel_hi:[1,0,1]
	v_lshl_add_u64 v[18:19], s[62:63], 0, v[150:151]
	v_pk_fma_f32 v[12:13], v[24:25], 0.5, v[128:129] op_sel_hi:[1,0,1]
	v_pk_fma_f32 v[10:11], v[22:23], 0.5, v[126:127] op_sel_hi:[1,0,1]
	v_lshl_add_u64 v[18:19], v[18:19], 0, v[146:147]
	v_pk_fma_f32 v[6:7], v[6:7], 0.5, v[114:115] op_sel_hi:[1,0,1]
	v_pk_fma_f32 v[16:17], v[16:17], 0.5, v[120:121] op_sel_hi:[1,0,1]
	v_pk_fma_f32 v[14:15], v[14:15], 0.5, v[118:119] op_sel_hi:[1,0,1]
	global_store_dwordx4 v[18:19], v[10:13], off nt
	global_store_dwordx4 v[18:19], v[14:17], off offset:16 nt
	v_pk_fma_f32 v[4:5], v[4:5], 0.5, v[108:109] op_sel_hi:[1,0,1]
	v_pk_fma_f32 v[2:3], v[2:3], 0.5, v[106:107] op_sel_hi:[1,0,1]
	global_store_dwordx4 v[18:19], v[6:9], off offset:512 nt
	global_store_dwordx4 v[18:19], v[2:5], off offset:528 nt
	s_cbranch_vccz .LBB0_4716
	s_waitcnt vmcnt(0)
	s_cmpk_gt_u32 s24, 0xff
	s_cbranch_scc1 .LBB0_4731
	s_barrier
